# first K-tile of every unit peeled: first-touch MFMAs take SrcC=0, the 128 v_mov accumulator zeroing per unit removed (GU, Down, mixer-in, mixer-out loops)
# speedup vs baseline: 1.0131x; 1.0131x over previous
; #define PG8_STAGE(bufoff, gbase, voff) do { _Pragma("unroll") for (int _i = 0; _i < 2; ++_i) \
;         __builtin_amdgcn_global_load_lds((const unsigned*)((const char*)(gbase) + (voff)[_i]), (PG8_LAS unsigned*)(lds + (bufoff) + ldsw + _i * 8192), 16, 0, 0); } while (0)
; #define PG8_LDA(dst, b, h) do { _Pragma("unroll") for (int m = 0; m < 4; ++m) _Pragma("unroll") for (int k = 0; k < 2; ++k) dst[m][k] = *(const PG8_LAS bf16x8*)(lds + PG8_SA(b, h) + aoff + m * 2048 + k * 1024); } while (0)
; #define PG8_LDB(dst, b, h) do { _Pragma("unroll") for (int n = 0; n < 2; ++n) _Pragma("unroll") for (int k = 0; k < 2; ++k) dst[n][k] = *(const PG8_LAS bf16x8*)(lds + PG8_SB(b, h) + boff + n * 2048 + k * 1024); } while (0)
; #define PG8_WAIT_V(n) asm volatile("s_waitcnt vmcnt(" #n ")" ::: "memory")
; #define PG8_WAIT_L(n) asm volatile("s_waitcnt lgkmcnt(" #n ")" ::: "memory")
; #define PG8_BAR __builtin_amdgcn_s_barrier()
; template <class Epi, class Sched, bool ALIGN_EPI = false, bool SP2 = true>
; __device__ __forceinline__ void gemm_phase(PG8_LAS unsigned char* lds, const Gemm g, const Sched& S, const Epi& E) {
;     ...
;         const bool has_next = S.next(ui + 1, nxt);
;         const char* nA = has_next ? (const char*)g.A + (size_t)nxt.pm * tstepA + (size_t)nxt.pn * pnA : cA; const char* nB = has_next ? (const char*)g.Bt + (size_t)nxt.pn * tstep : cB;
;         for (int t = 0; t < nt; t += 2) {
;             const bool last = (t == nt - 2);
;             const char* a1 = cA + (size_t)(t + 1) * kstepA;
;             const char* a2 = last ? nA : cA + (size_t)(t + 2) * kstepA; const char* b2 = last ? nB : cB + (size_t)(t + 2) * kstep;
;             const char* a3 = a2 + kstepA; const char* b3 = b2 + kstep;
;             if (last && has_next) S.a_ready(nxt);
;             if constexpr (SP2) {
;             PG8_LDB(B0, 0, 0); PG8_LDB(B1, 0, 1); PG8_SCHED; PG8_LDA(At, 0, 0); PG8_STAGE(PG8_SA(1, 1), a1 + hstepA, voffA);
;             PG8_WAIT_V(8); PG8_WAIT_L(0); PG8_BAR; PG8_MMA(0, 0, At, B0); PG8_MMA(0, 1, At, B1); PG8_BAR; PG8_SCHED;
;     ...
; #pragma unroll
;         for (int a = 0; a < 2; ++a)
; #pragma unroll
;             for (int b = 0; b < 2; ++b)
; #pragma unroll
;                 for (int m = 0; m < 4; ++m)
; #pragma unroll
;                     for (int n = 0; n < 2; ++n) acc[a][b][m][n] = (f32x4){0.f, 0.f, 0.f, 0.f};
;         cur = nxt; cA = nA; cB = nB; ++ui;
.LBB0_127:
	s_ashr_i32 s39, s38, 31
	s_lshl_b64 s[6:7], s[38:39], 19
	s_add_u32 s40, s54, s6
	s_addc_u32 s41, s55, s7
	s_and_b64 s[6:7], s[36:37], exec
	s_cselect_b32 s17, s41, s47
	s_cselect_b32 s39, s40, s46
	s_ashr_i32 s25, s24, 31
	s_lshl_b64 s[6:7], s[24:25], 19
	s_add_u32 s42, s26, s6
	s_addc_u32 s43, s27, s7
	s_and_b64 s[6:7], s[36:37], exec
	s_cselect_b32 s25, s43, s49
	s_cselect_b32 s59, s42, s48
	s_add_u32 s46, s46, 0x40080
	s_addc_u32 s47, s47, 0
	s_add_u32 s6, s48, 0x100
	s_addc_u32 s7, s49, 0
	s_mov_b32 s60, -2
	s_waitcnt lgkmcnt(0)
	s_add_u32 s14, s46, 0xfffc0080
	s_addc_u32 s15, s47, -1
	s_add_i32 s70, 0, 0x10000
	s_cmp_eq_u32 s60, 12
	s_cselect_b32 s51, s17, s15
	s_cselect_b32 s50, s39, s14
	v_add_u32_e32 v141, s70, v147
	s_cselect_b32 s49, s25, s7
	s_cselect_b32 s48, s59, s6
	s_add_i32 s71, 0, 0x14000
	ds_read_b128 v[152:155], v141
	ds_read_b128 v[156:159], v141 offset:1024
	ds_read_b128 v[160:163], v141 offset:2048
	ds_read_b128 v[164:167], v141 offset:3072
	v_add_u32_e32 v141, s71, v147
	ds_read_b128 v[168:171], v141
	ds_read_b128 v[172:175], v141 offset:1024
	ds_read_b128 v[176:179], v141 offset:2048
	ds_read_b128 v[180:183], v141 offset:3072
	s_add_u32 s14, s6, 0x3ff80
	s_addc_u32 s15, s7, 0
	v_lshl_add_u64 v[148:149], s[14:15], 0, v[132:133]
	s_add_i32 m0, s28, 0x1c000
	ds_read_b128 v[184:187], v150
	ds_read_b128 v[188:191], v150 offset:1024
	ds_read_b128 v[200:203], v150 offset:2048
	ds_read_b128 v[204:207], v150 offset:3072
	ds_read_b128 v[208:211], v150 offset:4096
	ds_read_b128 v[212:215], v150 offset:5120
	ds_read_b128 v[216:219], v150 offset:6144
	ds_read_b128 v[220:223], v150 offset:7168
	global_load_lds_dwordx4 v[148:149], off
	v_lshl_add_u64 v[148:149], s[14:15], 0, v[128:129]
	s_add_i32 m0, s28, 0x1e000
	s_nop 0
	global_load_lds_dwordx4 v[148:149], off
	v_lshl_add_u64 v[148:149], s[46:47], 0, v[136:137]
	s_add_i32 m0, s29, 0xc000
	s_nop 0
	global_load_lds_dwordx4 v[148:149], off
	v_lshl_add_u64 v[148:149], s[46:47], 0, v[138:139]
	s_add_i32 m0, s29, 0xe000
	s_nop 0
	global_load_lds_dwordx4 v[148:149], off
	s_waitcnt vmcnt(8)
	s_waitcnt lgkmcnt(0)
	s_setprio 1
	s_barrier
	v_mfma_f32_16x16x32_bf16 v[120:123], v[152:155], v[184:187], 0
	v_mfma_f32_16x16x32_bf16 v[112:115], v[160:163], v[184:187], 0
	v_mfma_f32_16x16x32_bf16 v[108:111], v[152:155], v[200:203], 0
	v_mfma_f32_16x16x32_bf16 v[96:99], v[160:163], v[200:203], 0
	v_mfma_f32_16x16x32_bf16 v[92:95], v[152:155], v[208:211], 0
	v_mfma_f32_16x16x32_bf16 v[80:83], v[160:163], v[208:211], 0
	v_mfma_f32_16x16x32_bf16 v[76:79], v[152:155], v[216:219], 0
	v_mfma_f32_16x16x32_bf16 v[64:67], v[160:163], v[216:219], 0
	v_mfma_f32_16x16x32_bf16 v[120:123], v[156:159], v[188:191], v[120:123]
	v_mfma_f32_16x16x32_bf16 v[112:115], v[164:167], v[188:191], v[112:115]
	v_mfma_f32_16x16x32_bf16 v[108:111], v[156:159], v[204:207], v[108:111]
	v_mfma_f32_16x16x32_bf16 v[96:99], v[164:167], v[204:207], v[96:99]
	v_mfma_f32_16x16x32_bf16 v[92:95], v[156:159], v[212:215], v[92:95]
	v_mfma_f32_16x16x32_bf16 v[80:83], v[164:167], v[212:215], v[80:83]
	v_mfma_f32_16x16x32_bf16 v[76:79], v[156:159], v[220:223], v[76:79]
	v_mfma_f32_16x16x32_bf16 v[64:67], v[164:167], v[220:223], v[64:67]
	v_mfma_f32_16x16x32_bf16 v[124:127], v[168:171], v[184:187], 0
	v_mfma_f32_16x16x32_bf16 v[116:119], v[176:179], v[184:187], 0
	v_mfma_f32_16x16x32_bf16 v[104:107], v[168:171], v[200:203], 0
	v_mfma_f32_16x16x32_bf16 v[100:103], v[176:179], v[200:203], 0
	v_mfma_f32_16x16x32_bf16 v[88:91], v[168:171], v[208:211], 0
	v_mfma_f32_16x16x32_bf16 v[84:87], v[176:179], v[208:211], 0
	v_mfma_f32_16x16x32_bf16 v[72:75], v[168:171], v[216:219], 0
	v_mfma_f32_16x16x32_bf16 v[68:71], v[176:179], v[216:219], 0
	v_mfma_f32_16x16x32_bf16 v[124:127], v[172:175], v[188:191], v[124:127]
	v_mfma_f32_16x16x32_bf16 v[116:119], v[180:183], v[188:191], v[116:119]
	v_mfma_f32_16x16x32_bf16 v[104:107], v[172:175], v[204:207], v[104:107]
	v_mfma_f32_16x16x32_bf16 v[100:103], v[180:183], v[204:207], v[100:103]
	v_mfma_f32_16x16x32_bf16 v[88:91], v[172:175], v[212:215], v[88:91]
	v_mfma_f32_16x16x32_bf16 v[84:87], v[180:183], v[212:215], v[84:87]
	v_mfma_f32_16x16x32_bf16 v[72:75], v[172:175], v[220:223], v[72:75]
	v_mfma_f32_16x16x32_bf16 v[68:71], v[180:183], v[220:223], v[68:71]
	s_setprio 0
	s_barrier
; #define PG8_STAGE(bufoff, gbase, voff) do { _Pragma("unroll") for (int _i = 0; _i < 2; ++_i) \
;         __builtin_amdgcn_global_load_lds((const unsigned*)((const char*)(gbase) + (voff)[_i]), (PG8_LAS unsigned*)(lds + (bufoff) + ldsw + _i * 8192), 16, 0, 0); } while (0)
; #define PG8_LDA(dst, b, h) do { _Pragma("unroll") for (int m = 0; m < 4; ++m) _Pragma("unroll") for (int k = 0; k < 2; ++k) dst[m][k] = *(const PG8_LAS bf16x8*)(lds + PG8_SA(b, h) + aoff + m * 2048 + k * 1024); } while (0)
; #define PG8_MMA(ai, bj, At, Bt) do { __builtin_amdgcn_s_setprio(1); _Pragma("unroll") for (int m = 0; m < 4; ++m) _Pragma("unroll") for (int n = 0; n < 2; ++n) _Pragma("unroll") for (int k = 0; k < 2; ++k) \
;         acc[ai][bj][m][n] = __builtin_amdgcn_mfma_f32_16x16x32_bf16(Bt[n][k], At[m][k], acc[ai][bj][m][n], 0, 0, 0); __builtin_amdgcn_s_setprio(0); } while (0)
; #define PG8_WAIT_V(n) asm volatile("s_waitcnt vmcnt(" #n ")" ::: "memory")
; #define PG8_WAIT_L(n) asm volatile("s_waitcnt lgkmcnt(" #n ")" ::: "memory")
; #define PG8_BAR __builtin_amdgcn_s_barrier()
; #define PG8_SCHED __builtin_amdgcn_sched_barrier(0)
; template <class Epi, class Sched, bool ALIGN_EPI = false, bool SP2 = true>
; __device__ __forceinline__ void gemm_phase(PG8_LAS unsigned char* lds, const Gemm g, const Sched& S, const Epi& E) {
;     ...
;             PG8_LDA(At, 0, 1); PG8_STAGE(PG8_SB(0, 0), b2, voffB); PG8_STAGE(PG8_SB(0, 1), b2 + hstep, voffB); PG8_STAGE(PG8_SA(0, 0), a2, voffA);
;             PG8_WAIT_V(8); PG8_WAIT_L(0); PG8_BAR; PG8_MMA(1, 0, At, B0); PG8_MMA(1, 1, At, B1); PG8_BAR; PG8_SCHED;
	s_add_i32 s14, s70, s28
	v_lshl_add_u64 v[148:149], s[48:49], 0, v[132:133]
	s_mov_b32 m0, s14
	ds_read_b128 v[184:187], v150 offset:16384
	ds_read_b128 v[188:191], v150 offset:17408
	ds_read_b128 v[200:203], v150 offset:18432
	ds_read_b128 v[204:207], v150 offset:19456
	ds_read_b128 v[208:211], v150 offset:20480
	ds_read_b128 v[212:215], v150 offset:21504
	ds_read_b128 v[216:219], v150 offset:22528
	ds_read_b128 v[220:223], v150 offset:23552
	global_load_lds_dwordx4 v[148:149], off
	s_add_i32 m0, s14, 0x2000
	v_lshl_add_u64 v[224:225], s[48:49], 0, v[128:129]
	global_load_lds_dwordx4 v[224:225], off
	v_lshl_add_u64 v[234:235], s[50:51], 0, v[130:131]
	v_lshl_add_u64 v[226:227], s[50:51], 0, v[134:135]
	s_mov_b32 m0, s29
	s_nop 0
	global_load_lds_dwordx4 v[226:227], off
	s_mov_b32 m0, s30
	s_nop 0
	global_load_lds_dwordx4 v[234:235], off
	s_waitcnt vmcnt(6)
	s_waitcnt lgkmcnt(0)
	s_setprio 1
	s_barrier
	v_mfma_f32_16x16x32_bf16 v[60:63], v[152:155], v[184:187], 0
	v_mfma_f32_16x16x32_bf16 v[48:51], v[160:163], v[184:187], 0
	v_mfma_f32_16x16x32_bf16 v[44:47], v[152:155], v[200:203], 0
	v_mfma_f32_16x16x32_bf16 v[32:35], v[160:163], v[200:203], 0
	v_mfma_f32_16x16x32_bf16 v[28:31], v[152:155], v[208:211], 0
	v_mfma_f32_16x16x32_bf16 v[16:19], v[160:163], v[208:211], 0
	v_mfma_f32_16x16x32_bf16 v[12:15], v[152:155], v[216:219], 0
	v_mfma_f32_16x16x32_bf16 v[4:7], v[160:163], v[216:219], 0
	v_mfma_f32_16x16x32_bf16 v[60:63], v[156:159], v[188:191], v[60:63]
	v_mfma_f32_16x16x32_bf16 v[48:51], v[164:167], v[188:191], v[48:51]
	v_mfma_f32_16x16x32_bf16 v[44:47], v[156:159], v[204:207], v[44:47]
	v_mfma_f32_16x16x32_bf16 v[32:35], v[164:167], v[204:207], v[32:35]
	v_mfma_f32_16x16x32_bf16 v[28:31], v[156:159], v[212:215], v[28:31]
	v_mfma_f32_16x16x32_bf16 v[16:19], v[164:167], v[212:215], v[16:19]
	v_mfma_f32_16x16x32_bf16 v[12:15], v[156:159], v[220:223], v[12:15]
	v_mfma_f32_16x16x32_bf16 v[4:7], v[164:167], v[220:223], v[4:7]
	v_mfma_f32_16x16x32_bf16 v[56:59], v[168:171], v[184:187], 0
	v_mfma_f32_16x16x32_bf16 v[52:55], v[176:179], v[184:187], 0
	v_mfma_f32_16x16x32_bf16 v[40:43], v[168:171], v[200:203], 0
	v_mfma_f32_16x16x32_bf16 v[36:39], v[176:179], v[200:203], 0
	v_mfma_f32_16x16x32_bf16 v[24:27], v[168:171], v[208:211], 0
	v_mfma_f32_16x16x32_bf16 v[20:23], v[176:179], v[208:211], 0
	v_mfma_f32_16x16x32_bf16 v[8:11], v[168:171], v[216:219], 0
	v_mfma_f32_16x16x32_bf16 v[0:3], v[176:179], v[216:219], 0
	v_mfma_f32_16x16x32_bf16 v[56:59], v[172:175], v[188:191], v[56:59]
	v_mfma_f32_16x16x32_bf16 v[52:55], v[180:183], v[188:191], v[52:55]
	v_mfma_f32_16x16x32_bf16 v[40:43], v[172:175], v[204:207], v[40:43]
	v_mfma_f32_16x16x32_bf16 v[36:39], v[180:183], v[204:207], v[36:39]
	v_mfma_f32_16x16x32_bf16 v[24:27], v[172:175], v[212:215], v[24:27]
	v_mfma_f32_16x16x32_bf16 v[20:23], v[180:183], v[212:215], v[20:23]
	v_mfma_f32_16x16x32_bf16 v[8:11], v[172:175], v[220:223], v[8:11]
	v_mfma_f32_16x16x32_bf16 v[0:3], v[180:183], v[220:223], v[0:3]
	s_setprio 0
	s_barrier
	s_branch .Lgu_s3

; #define PG8_STAGE(bufoff, gbase, voff) do { _Pragma("unroll") for (int _i = 0; _i < 2; ++_i) \
;         __builtin_amdgcn_global_load_lds((const unsigned*)((const char*)(gbase) + (voff)[_i]), (PG8_LAS unsigned*)(lds + (bufoff) + ldsw + _i * 8192), 16, 0, 0); } while (0)
; #define PG8_LDA(dst, b, h) do { _Pragma("unroll") for (int m = 0; m < 4; ++m) _Pragma("unroll") for (int k = 0; k < 2; ++k) dst[m][k] = *(const PG8_LAS bf16x8*)(lds + PG8_SA(b, h) + aoff + m * 2048 + k * 1024); } while (0)
; #define PG8_LDB(dst, b, h) do { _Pragma("unroll") for (int n = 0; n < 2; ++n) _Pragma("unroll") for (int k = 0; k < 2; ++k) dst[n][k] = *(const PG8_LAS bf16x8*)(lds + PG8_SB(b, h) + boff + n * 2048 + k * 1024); } while (0)
; #define PG8_MMA(ai, bj, At, Bt) do { __builtin_amdgcn_s_setprio(1); _Pragma("unroll") for (int m = 0; m < 4; ++m) _Pragma("unroll") for (int n = 0; n < 2; ++n) _Pragma("unroll") for (int k = 0; k < 2; ++k) \
;         acc[ai][bj][m][n] = __builtin_amdgcn_mfma_f32_16x16x32_bf16(Bt[n][k], At[m][k], acc[ai][bj][m][n], 0, 0, 0); __builtin_amdgcn_s_setprio(0); } while (0)
; #define PG8_WAIT_V(n) asm volatile("s_waitcnt vmcnt(" #n ")" ::: "memory")
; #define PG8_WAIT_L(n) asm volatile("s_waitcnt lgkmcnt(" #n ")" ::: "memory")
; #define PG8_BAR __builtin_amdgcn_s_barrier()
; #define PG8_SCHED __builtin_amdgcn_sched_barrier(0)
;     __device__ __forceinline__ void operator()(const f32x4 (&acc)[2][2][4][2], const Unit& u, int wr, int wc, int fr, int fq) const {
;     ...
;             for (int m = 0; m < 4; ++m) sv[ai][m] = ssq[row0 + ai * HALF + m * 16];
; template <class Epi, class Sched, bool ALIGN_EPI = false, bool SP2 = true>
; __device__ __forceinline__ void gemm_phase(PG8_LAS unsigned char* lds, const Gemm g, const Sched& S, const Epi& E) {
;     ...
;             PG8_LDB(B0, 1, 0); PG8_LDB(B1, 1, 1); PG8_SCHED; PG8_LDA(At, 1, 0); PG8_STAGE(PG8_SA(0, 1), a2 + hstepA, voffA);
;             PG8_WAIT_V(8); PG8_WAIT_L(0); PG8_BAR; PG8_MMA(0, 0, At, B0); PG8_MMA(0, 1, At, B1); PG8_BAR; PG8_SCHED;
;             PG8_LDA(At, 1, 1); PG8_STAGE(PG8_SB(1, 0), b3, voffB); PG8_STAGE(PG8_SB(1, 1), b3 + hstep, voffB); PG8_STAGE(PG8_SA(1, 0), a3, voffA);
;             PG8_WAIT_V(8); PG8_WAIT_L(0); PG8_BAR; PG8_MMA(1, 0, At, B0); PG8_MMA(1, 1, At, B1); PG8_BAR; PG8_SCHED;
.Lgu_s3:
	s_add_i32 s70, 0, 0x18000
	v_add_u32_e32 v141, s70, v147
	s_add_i32 s71, 0, 0x1c000
	ds_read_b128 v[152:155], v141
	ds_read_b128 v[156:159], v141 offset:1024
	ds_read_b128 v[160:163], v141 offset:2048
	ds_read_b128 v[164:167], v141 offset:3072
	v_add_u32_e32 v141, s71, v147
	ds_read_b128 v[168:171], v141
	ds_read_b128 v[172:175], v141 offset:1024
	ds_read_b128 v[176:179], v141 offset:2048
	ds_read_b128 v[180:183], v141 offset:3072
	s_add_u32 s14, s48, 0x40000
	s_addc_u32 s15, s49, 0
	s_add_i32 m0, s28, 0x14000
	v_lshl_add_u64 v[236:237], s[14:15], 0, v[132:133]
	ds_read_b128 v[184:187], v150 offset:32768
	ds_read_b128 v[188:191], v150 offset:33792
	ds_read_b128 v[200:203], v150 offset:34816
	ds_read_b128 v[204:207], v150 offset:35840
	ds_read_b128 v[208:211], v150 offset:36864
	ds_read_b128 v[212:215], v150 offset:37888
	ds_read_b128 v[216:219], v150 offset:38912
	ds_read_b128 v[220:223], v150 offset:39936
	global_load_lds_dwordx4 v[236:237], off
	v_lshl_add_u64 v[236:237], s[14:15], 0, v[128:129]
	s_add_i32 m0, s28, 0x16000
	s_add_u32 s14, s50, 0x40000
	s_addc_u32 s15, s51, 0
	global_load_lds_dwordx4 v[236:237], off
	v_lshl_add_u64 v[236:237], s[14:15], 0, v[134:135]
	s_mov_b32 m0, s31
	s_nop 0
	global_load_lds_dwordx4 v[236:237], off
	v_lshl_add_u64 v[236:237], s[14:15], 0, v[130:131]
	s_mov_b32 m0, s34
	s_nop 0
	global_load_lds_dwordx4 v[236:237], off
	s_waitcnt vmcnt(8)
	s_waitcnt lgkmcnt(0)
	s_setprio 1
	s_barrier
	v_mfma_f32_16x16x32_bf16 v[120:123], v[152:155], v[184:187], v[120:123]
	v_mfma_f32_16x16x32_bf16 v[112:115], v[160:163], v[184:187], v[112:115]
	v_mfma_f32_16x16x32_bf16 v[108:111], v[152:155], v[200:203], v[108:111]
	v_mfma_f32_16x16x32_bf16 v[96:99], v[160:163], v[200:203], v[96:99]
	v_mfma_f32_16x16x32_bf16 v[92:95], v[152:155], v[208:211], v[92:95]
	v_mfma_f32_16x16x32_bf16 v[80:83], v[160:163], v[208:211], v[80:83]
	v_mfma_f32_16x16x32_bf16 v[76:79], v[152:155], v[216:219], v[76:79]
	v_mfma_f32_16x16x32_bf16 v[64:67], v[160:163], v[216:219], v[64:67]
	v_mfma_f32_16x16x32_bf16 v[120:123], v[156:159], v[188:191], v[120:123]
	v_mfma_f32_16x16x32_bf16 v[112:115], v[164:167], v[188:191], v[112:115]
	v_mfma_f32_16x16x32_bf16 v[108:111], v[156:159], v[204:207], v[108:111]
	v_mfma_f32_16x16x32_bf16 v[96:99], v[164:167], v[204:207], v[96:99]
	v_mfma_f32_16x16x32_bf16 v[92:95], v[156:159], v[212:215], v[92:95]
	v_mfma_f32_16x16x32_bf16 v[80:83], v[164:167], v[212:215], v[80:83]
	v_mfma_f32_16x16x32_bf16 v[76:79], v[156:159], v[220:223], v[76:79]
	v_mfma_f32_16x16x32_bf16 v[64:67], v[164:167], v[220:223], v[64:67]
	v_mfma_f32_16x16x32_bf16 v[124:127], v[168:171], v[184:187], v[124:127]
	v_mfma_f32_16x16x32_bf16 v[116:119], v[176:179], v[184:187], v[116:119]
	v_mfma_f32_16x16x32_bf16 v[104:107], v[168:171], v[200:203], v[104:107]
	v_mfma_f32_16x16x32_bf16 v[100:103], v[176:179], v[200:203], v[100:103]
	v_mfma_f32_16x16x32_bf16 v[88:91], v[168:171], v[208:211], v[88:91]
	v_mfma_f32_16x16x32_bf16 v[84:87], v[176:179], v[208:211], v[84:87]
	v_mfma_f32_16x16x32_bf16 v[72:75], v[168:171], v[216:219], v[72:75]
	v_mfma_f32_16x16x32_bf16 v[68:71], v[176:179], v[216:219], v[68:71]
	v_mfma_f32_16x16x32_bf16 v[124:127], v[172:175], v[188:191], v[124:127]
	v_mfma_f32_16x16x32_bf16 v[116:119], v[180:183], v[188:191], v[116:119]
	v_mfma_f32_16x16x32_bf16 v[104:107], v[172:175], v[204:207], v[104:107]
	v_mfma_f32_16x16x32_bf16 v[100:103], v[180:183], v[204:207], v[100:103]
	v_mfma_f32_16x16x32_bf16 v[88:91], v[172:175], v[212:215], v[88:91]
	v_mfma_f32_16x16x32_bf16 v[84:87], v[180:183], v[212:215], v[84:87]
	v_mfma_f32_16x16x32_bf16 v[72:75], v[172:175], v[220:223], v[72:75]
	v_mfma_f32_16x16x32_bf16 v[68:71], v[180:183], v[220:223], v[68:71]
	s_setprio 0
	s_barrier
	s_add_i32 s14, s70, s28
	v_lshl_add_u64 v[148:149], v[148:149], 0, s[18:19]
	s_mov_b32 m0, s14
	ds_read_b128 v[184:187], v150 offset:49152
	ds_read_b128 v[188:191], v150 offset:50176
	ds_read_b128 v[200:203], v150 offset:51200
	ds_read_b128 v[204:207], v150 offset:52224
	ds_read_b128 v[208:211], v150 offset:53248
	ds_read_b128 v[212:215], v150 offset:54272
	ds_read_b128 v[216:219], v150 offset:55296
	ds_read_b128 v[220:223], v150 offset:56320
	global_load_lds_dwordx4 v[148:149], off
	s_add_i32 m0, s14, 0x2000
	v_lshl_add_u64 v[148:149], v[224:225], 0, s[18:19]
	global_load_lds_dwordx4 v[148:149], off
	v_lshl_add_u64 v[148:149], v[226:227], 0, s[18:19]
	s_mov_b32 m0, s52
	s_nop 0
	global_load_lds_dwordx4 v[148:149], off
	v_lshl_add_u64 v[148:149], v[234:235], 0, s[18:19]
	s_mov_b32 m0, s53
	s_nop 0
	global_load_lds_dwordx4 v[148:149], off
	s_waitcnt vmcnt(6)
	s_waitcnt lgkmcnt(0)
	s_cmp_lg_u32 s60, 12
	s_cbranch_scc1 .Lgu_no_ssq_prefetch
	v_lshl_add_u32 v148, s58, 8, v145
	v_ashrrev_i32_e32 v149, 31, v148
	v_lshl_add_u64 v[148:149], v[148:149], 3, s[10:11]
	global_load_dwordx2 v[238:239], v[148:149], off
	global_load_dwordx2 v[240:241], v[148:149], off offset:128
	global_load_dwordx2 v[242:243], v[148:149], off offset:256
	global_load_dwordx2 v[244:245], v[148:149], off offset:384
	global_load_dwordx2 v[246:247], v[148:149], off offset:1024
	global_load_dwordx2 v[248:249], v[148:149], off offset:1152
	global_load_dwordx2 v[250:251], v[148:149], off offset:1280
	global_load_dwordx2 v[228:229], v[148:149], off offset:1408

; #define PG8_STAGE(bufoff, gbase, voff) do { _Pragma("unroll") for (int _i = 0; _i < 2; ++_i) \
;         __builtin_amdgcn_global_load_lds((const unsigned*)((const char*)(gbase) + (voff)[_i]), (PG8_LAS unsigned*)(lds + (bufoff) + ldsw + _i * 8192), 16, 0, 0); } while (0)
; #define PG8_LDA(dst, b, h) do { _Pragma("unroll") for (int m = 0; m < 4; ++m) _Pragma("unroll") for (int k = 0; k < 2; ++k) dst[m][k] = *(const PG8_LAS bf16x8*)(lds + PG8_SA(b, h) + aoff + m * 2048 + k * 1024); } while (0)
; #define PG8_LDB(dst, b, h) do { _Pragma("unroll") for (int n = 0; n < 2; ++n) _Pragma("unroll") for (int k = 0; k < 2; ++k) dst[n][k] = *(const PG8_LAS bf16x8*)(lds + PG8_SB(b, h) + boff + n * 2048 + k * 1024); } while (0)
; #define PG8_WAIT_V(n) asm volatile("s_waitcnt vmcnt(" #n ")" ::: "memory")
; #define PG8_WAIT_L(n) asm volatile("s_waitcnt lgkmcnt(" #n ")" ::: "memory")
; #define PG8_BAR __builtin_amdgcn_s_barrier()
; #define PG8_SCHED __builtin_amdgcn_sched_barrier(0)
; template <class Epi, class Sched, bool ALIGN_EPI = false, bool SP2 = true>
; __device__ __forceinline__ void gemm_phase(PG8_LAS unsigned char* lds, const Gemm g, const Sched& S, const Epi& E) {
;     ...
;         const bool has_next = S.next(ui + 1, nxt);
;         const char* nA = has_next ? (const char*)g.A + (size_t)nxt.pm * tstepA + (size_t)nxt.pn * pnA : cA; const char* nB = has_next ? (const char*)g.Bt + (size_t)nxt.pn * tstep : cB;
;         for (int t = 0; t < nt; t += 2) {
;             const bool last = (t == nt - 2);
;             const char* a1 = cA + (size_t)(t + 1) * kstepA;
;             const char* a2 = last ? nA : cA + (size_t)(t + 2) * kstepA; const char* b2 = last ? nB : cB + (size_t)(t + 2) * kstep;
;             const char* a3 = a2 + kstepA; const char* b3 = b2 + kstep;
;             if (last && has_next) S.a_ready(nxt);
;             if constexpr (SP2) {
;             PG8_LDB(B0, 0, 0); PG8_LDB(B1, 0, 1); PG8_SCHED; PG8_LDA(At, 0, 0); PG8_STAGE(PG8_SA(1, 1), a1 + hstepA, voffA);
;             PG8_WAIT_V(8); PG8_WAIT_L(0); PG8_BAR; PG8_MMA(0, 0, At, B0); PG8_MMA(0, 1, At, B1); PG8_BAR; PG8_SCHED;
;     ...
;         for (int a = 0; a < 2; ++a)
; #pragma unroll
;             for (int b = 0; b < 2; ++b)
; #pragma unroll
;                 for (int m = 0; m < 4; ++m)
; #pragma unroll
;                     for (int n = 0; n < 2; ++n) acc[a][b][m][n] = (f32x4){0.f, 0.f, 0.f, 0.f};
.LBB0_235:
	s_add_u32 s42, s42, 0xc000
	s_addc_u32 s43, s43, 0
	s_add_u32 s17, s46, 0x100
	s_addc_u32 s6, s47, 0
	s_mov_b32 s7, -2
	s_waitcnt lgkmcnt(0)
	s_add_u32 s14, s42, 0x4000
	s_addc_u32 s15, s43, 0
	s_cmp_eq_u32 s7, 40
	s_cselect_b32 s84, s10, s14
	s_cselect_b32 s85, s11, s15
	s_cselect_b32 vcc_lo, s52, s17
	s_cselect_b32 vcc_hi, s53, s6
	s_add_u32 s46, s84, 0x8000
	s_addc_u32 s47, s85, 0
	s_add_i32 s14, 0, 0x10000
	s_add_i32 s4, 0, 0x14000
	v_add_u32_e32 v140, s14, v235
	v_add_u32_e32 v156, s4, v235
	ds_read_b128 v[128:131], v140
	ds_read_b128 v[132:135], v140 offset:1024
	ds_read_b128 v[136:139], v140 offset:2048
	ds_read_b128 v[140:143], v140 offset:3072
	ds_read_b128 v[144:147], v156
	ds_read_b128 v[148:151], v156 offset:1024
	ds_read_b128 v[152:155], v156 offset:2048
	ds_read_b128 v[156:159], v156 offset:3072
	v_lshl_add_u64 v[212:213], s[42:43], 0, v[208:209]
	s_add_i32 m0, s59, 0xc000
	ds_read_b128 v[160:163], v237
	ds_read_b128 v[164:167], v237 offset:1024
	ds_read_b128 v[168:171], v237 offset:2048
	ds_read_b128 v[172:175], v237 offset:3072
	ds_read_b128 v[176:179], v237 offset:4096
	ds_read_b128 v[180:183], v237 offset:5120
	ds_read_b128 v[184:187], v237 offset:6144
	ds_read_b128 v[188:191], v237 offset:7168
	global_load_lds_dwordx4 v[212:213], off
	v_lshl_add_u64 v[212:213], s[42:43], 0, v[210:211]
	s_add_i32 m0, s59, 0xe000
	s_nop 0
	global_load_lds_dwordx4 v[212:213], off
	s_waitcnt vmcnt(8)
	s_waitcnt lgkmcnt(0)
	s_setprio 1
	s_barrier
	v_mfma_f32_16x16x32_bf16 v[124:127], v[128:131], v[160:163], 0
	v_mfma_f32_16x16x32_bf16 v[120:123], v[136:139], v[160:163], 0
	v_mfma_f32_16x16x32_bf16 v[108:111], v[128:131], v[168:171], 0
	v_mfma_f32_16x16x32_bf16 v[104:107], v[136:139], v[168:171], 0
	v_mfma_f32_16x16x32_bf16 v[92:95], v[128:131], v[176:179], 0
	v_mfma_f32_16x16x32_bf16 v[88:91], v[136:139], v[176:179], 0
	v_mfma_f32_16x16x32_bf16 v[76:79], v[128:131], v[184:187], 0
	v_mfma_f32_16x16x32_bf16 v[72:75], v[136:139], v[184:187], 0
	v_mfma_f32_16x16x32_bf16 v[124:127], v[132:135], v[164:167], v[124:127]
	v_mfma_f32_16x16x32_bf16 v[120:123], v[140:143], v[164:167], v[120:123]
	v_mfma_f32_16x16x32_bf16 v[108:111], v[132:135], v[172:175], v[108:111]
	v_mfma_f32_16x16x32_bf16 v[104:107], v[140:143], v[172:175], v[104:107]
	v_mfma_f32_16x16x32_bf16 v[92:95], v[132:135], v[180:183], v[92:95]
	v_mfma_f32_16x16x32_bf16 v[88:91], v[140:143], v[180:183], v[88:91]
	v_mfma_f32_16x16x32_bf16 v[76:79], v[132:135], v[188:191], v[76:79]
	v_mfma_f32_16x16x32_bf16 v[72:75], v[140:143], v[188:191], v[72:75]
	s_setprio 0
	s_setprio 1
	v_mfma_f32_16x16x32_bf16 v[116:119], v[144:147], v[160:163], 0
	v_mfma_f32_16x16x32_bf16 v[112:115], v[152:155], v[160:163], 0
	v_mfma_f32_16x16x32_bf16 v[100:103], v[144:147], v[168:171], 0
	v_mfma_f32_16x16x32_bf16 v[96:99], v[152:155], v[168:171], 0
	v_mfma_f32_16x16x32_bf16 v[84:87], v[144:147], v[176:179], 0
	v_mfma_f32_16x16x32_bf16 v[80:83], v[152:155], v[176:179], 0
	v_mfma_f32_16x16x32_bf16 v[68:71], v[144:147], v[184:187], 0
	v_mfma_f32_16x16x32_bf16 v[64:67], v[152:155], v[184:187], 0
	v_mfma_f32_16x16x32_bf16 v[116:119], v[148:151], v[164:167], v[116:119]
	v_mfma_f32_16x16x32_bf16 v[112:115], v[156:159], v[164:167], v[112:115]
	v_mfma_f32_16x16x32_bf16 v[100:103], v[148:151], v[172:175], v[100:103]
	v_mfma_f32_16x16x32_bf16 v[96:99], v[156:159], v[172:175], v[96:99]
	v_mfma_f32_16x16x32_bf16 v[84:87], v[148:151], v[180:183], v[84:87]
	v_mfma_f32_16x16x32_bf16 v[80:83], v[156:159], v[180:183], v[80:83]
	v_mfma_f32_16x16x32_bf16 v[68:71], v[148:151], v[188:191], v[68:71]
	v_mfma_f32_16x16x32_bf16 v[64:67], v[156:159], v[188:191], v[64:67]
	s_setprio 0
	s_barrier
; #define PG8_STAGE(bufoff, gbase, voff) do { _Pragma("unroll") for (int _i = 0; _i < 2; ++_i) \
;         __builtin_amdgcn_global_load_lds((const unsigned*)((const char*)(gbase) + (voff)[_i]), (PG8_LAS unsigned*)(lds + (bufoff) + ldsw + _i * 8192), 16, 0, 0); } while (0)
; #define PG8_LDA(dst, b, h) do { _Pragma("unroll") for (int m = 0; m < 4; ++m) _Pragma("unroll") for (int k = 0; k < 2; ++k) dst[m][k] = *(const PG8_LAS bf16x8*)(lds + PG8_SA(b, h) + aoff + m * 2048 + k * 1024); } while (0)
; #define PG8_MMA(ai, bj, At, Bt) do { __builtin_amdgcn_s_setprio(1); _Pragma("unroll") for (int m = 0; m < 4; ++m) _Pragma("unroll") for (int n = 0; n < 2; ++n) _Pragma("unroll") for (int k = 0; k < 2; ++k) \
;         acc[ai][bj][m][n] = __builtin_amdgcn_mfma_f32_16x16x32_bf16(Bt[n][k], At[m][k], acc[ai][bj][m][n], 0, 0, 0); __builtin_amdgcn_s_setprio(0); } while (0)
; #define PG8_WAIT_V(n) asm volatile("s_waitcnt vmcnt(" #n ")" ::: "memory")
; #define PG8_WAIT_L(n) asm volatile("s_waitcnt lgkmcnt(" #n ")" ::: "memory")
; #define PG8_BAR __builtin_amdgcn_s_barrier()
; #define PG8_SCHED __builtin_amdgcn_sched_barrier(0)
; template <class Epi, class Sched, bool ALIGN_EPI = false, bool SP2 = true>
; __device__ __forceinline__ void gemm_phase(PG8_LAS unsigned char* lds, const Gemm g, const Sched& S, const Epi& E) {
;     ...
;             PG8_LDA(At, 0, 1); PG8_STAGE(PG8_SB(0, 0), b2, voffB); PG8_STAGE(PG8_SB(0, 1), b2 + hstep, voffB); PG8_STAGE(PG8_SA(0, 0), a2, voffA);
;             PG8_WAIT_V(8); PG8_WAIT_L(0); PG8_BAR; PG8_MMA(1, 0, At, B0); PG8_MMA(1, 1, At, B1); PG8_BAR; PG8_SCHED;
	s_add_i32 s5, s14, s57
	v_lshl_add_u64 v[212:213], vcc, 0, v[194:195]
	s_mov_b32 m0, s5
	ds_read_b128 v[160:163], v237 offset:16384
	ds_read_b128 v[164:167], v237 offset:17408
	ds_read_b128 v[168:171], v237 offset:18432
	ds_read_b128 v[172:175], v237 offset:19456
	ds_read_b128 v[176:179], v237 offset:20480
	ds_read_b128 v[180:183], v237 offset:21504
	ds_read_b128 v[184:187], v237 offset:22528
	ds_read_b128 v[188:191], v237 offset:23552
	global_load_lds_dwordx4 v[212:213], off
	s_add_i32 m0, s5, 0x2000
	s_add_u32 s14, vcc_lo, 0xb0000
	v_lshl_add_u64 v[214:215], vcc, 0, v[204:205]
	s_addc_u32 s15, vcc_hi, 0
	s_add_i32 s4, s4, s57
	global_load_lds_dwordx4 v[214:215], off
	v_lshl_add_u64 v[216:217], s[14:15], 0, v[194:195]
	s_mov_b32 m0, s4
	s_nop 0
	global_load_lds_dwordx4 v[216:217], off
	v_lshl_add_u64 v[216:217], s[14:15], 0, v[204:205]
	s_add_i32 m0, s4, 0x2000
	s_nop 0
	global_load_lds_dwordx4 v[216:217], off
	v_lshl_add_u64 v[216:217], s[84:85], 0, v[200:201]
	s_mov_b32 m0, s59
	s_nop 0
	global_load_lds_dwordx4 v[216:217], off
	v_lshl_add_u64 v[216:217], s[84:85], 0, v[202:203]
	s_mov_b32 m0, s60
	s_nop 0
	global_load_lds_dwordx4 v[216:217], off
	s_waitcnt vmcnt(8)
	s_waitcnt lgkmcnt(0)
	s_setprio 1
	s_barrier
	v_mfma_f32_16x16x32_bf16 v[60:63], v[128:131], v[160:163], 0
	v_mfma_f32_16x16x32_bf16 v[56:59], v[136:139], v[160:163], 0
	v_mfma_f32_16x16x32_bf16 v[44:47], v[128:131], v[168:171], 0
	v_mfma_f32_16x16x32_bf16 v[40:43], v[136:139], v[168:171], 0
	v_mfma_f32_16x16x32_bf16 v[28:31], v[128:131], v[176:179], 0
	v_mfma_f32_16x16x32_bf16 v[24:27], v[136:139], v[176:179], 0
	v_mfma_f32_16x16x32_bf16 v[12:15], v[128:131], v[184:187], 0
	v_mfma_f32_16x16x32_bf16 v[8:11], v[136:139], v[184:187], 0
	v_mfma_f32_16x16x32_bf16 v[60:63], v[132:135], v[164:167], v[60:63]
	v_mfma_f32_16x16x32_bf16 v[56:59], v[140:143], v[164:167], v[56:59]
	v_mfma_f32_16x16x32_bf16 v[44:47], v[132:135], v[172:175], v[44:47]
	v_mfma_f32_16x16x32_bf16 v[40:43], v[140:143], v[172:175], v[40:43]
	v_mfma_f32_16x16x32_bf16 v[28:31], v[132:135], v[180:183], v[28:31]
	v_mfma_f32_16x16x32_bf16 v[24:27], v[140:143], v[180:183], v[24:27]
	v_mfma_f32_16x16x32_bf16 v[12:15], v[132:135], v[188:191], v[12:15]
	v_mfma_f32_16x16x32_bf16 v[8:11], v[140:143], v[188:191], v[8:11]
	s_setprio 0
	s_setprio 1
	v_mfma_f32_16x16x32_bf16 v[52:55], v[144:147], v[160:163], 0
	v_mfma_f32_16x16x32_bf16 v[48:51], v[152:155], v[160:163], 0
	v_mfma_f32_16x16x32_bf16 v[36:39], v[144:147], v[168:171], 0
	v_mfma_f32_16x16x32_bf16 v[32:35], v[152:155], v[168:171], 0
	v_mfma_f32_16x16x32_bf16 v[20:23], v[144:147], v[176:179], 0
	v_mfma_f32_16x16x32_bf16 v[16:19], v[152:155], v[176:179], 0
	v_mfma_f32_16x16x32_bf16 v[4:7], v[144:147], v[184:187], 0
	v_mfma_f32_16x16x32_bf16 v[0:3], v[152:155], v[184:187], 0
	v_mfma_f32_16x16x32_bf16 v[52:55], v[148:151], v[164:167], v[52:55]
	v_mfma_f32_16x16x32_bf16 v[48:51], v[156:159], v[164:167], v[48:51]
	v_mfma_f32_16x16x32_bf16 v[36:39], v[148:151], v[172:175], v[36:39]
	v_mfma_f32_16x16x32_bf16 v[32:35], v[156:159], v[172:175], v[32:35]
	v_mfma_f32_16x16x32_bf16 v[20:23], v[148:151], v[180:183], v[20:23]
	v_mfma_f32_16x16x32_bf16 v[16:19], v[156:159], v[180:183], v[16:19]
	v_mfma_f32_16x16x32_bf16 v[4:7], v[148:151], v[188:191], v[4:7]
	v_mfma_f32_16x16x32_bf16 v[0:3], v[156:159], v[188:191], v[0:3]
	s_setprio 0
	s_barrier
	s_branch .Ldn_s3

; #define PG8_STAGE(bufoff, gbase, voff) do { _Pragma("unroll") for (int _i = 0; _i < 2; ++_i) \
;         __builtin_amdgcn_global_load_lds((const unsigned*)((const char*)(gbase) + (voff)[_i]), (PG8_LAS unsigned*)(lds + (bufoff) + ldsw + _i * 8192), 16, 0, 0); } while (0)
; #define PG8_LDA(dst, b, h) do { _Pragma("unroll") for (int m = 0; m < 4; ++m) _Pragma("unroll") for (int k = 0; k < 2; ++k) dst[m][k] = *(const PG8_LAS bf16x8*)(lds + PG8_SA(b, h) + aoff + m * 2048 + k * 1024); } while (0)
; #define PG8_LDB(dst, b, h) do { _Pragma("unroll") for (int n = 0; n < 2; ++n) _Pragma("unroll") for (int k = 0; k < 2; ++k) dst[n][k] = *(const PG8_LAS bf16x8*)(lds + PG8_SB(b, h) + boff + n * 2048 + k * 1024); } while (0)
; #define PG8_MMA(ai, bj, At, Bt) do { __builtin_amdgcn_s_setprio(1); _Pragma("unroll") for (int m = 0; m < 4; ++m) _Pragma("unroll") for (int n = 0; n < 2; ++n) _Pragma("unroll") for (int k = 0; k < 2; ++k) \
;         acc[ai][bj][m][n] = __builtin_amdgcn_mfma_f32_16x16x32_bf16(Bt[n][k], At[m][k], acc[ai][bj][m][n], 0, 0, 0); __builtin_amdgcn_s_setprio(0); } while (0)
; #define PG8_WAIT_V(n) asm volatile("s_waitcnt vmcnt(" #n ")" ::: "memory")
; #define PG8_WAIT_L(n) asm volatile("s_waitcnt lgkmcnt(" #n ")" ::: "memory")
; #define PG8_BAR __builtin_amdgcn_s_barrier()
; #define PG8_SCHED __builtin_amdgcn_sched_barrier(0)
; template <class Epi, class Sched, bool ALIGN_EPI = false, bool SP2 = true>
; __device__ __forceinline__ void gemm_phase(PG8_LAS unsigned char* lds, const Gemm g, const Sched& S, const Epi& E) {
;     ...
;             PG8_LDB(B0, 1, 0); PG8_LDB(B1, 1, 1); PG8_SCHED; PG8_LDA(At, 1, 0); PG8_STAGE(PG8_SA(0, 1), a2 + hstepA, voffA);
;             PG8_WAIT_V(8); PG8_WAIT_L(0); PG8_BAR; PG8_MMA(0, 0, At, B0); PG8_MMA(0, 1, At, B1); PG8_BAR; PG8_SCHED;
.Ldn_s3:
	s_add_i32 s4, 0, 0x18000
	s_add_i32 s5, 0, 0x1c000
	v_add_u32_e32 v140, s4, v235
	v_add_u32_e32 v156, s5, v235
	ds_read_b128 v[128:131], v140
	ds_read_b128 v[132:135], v140 offset:1024
	ds_read_b128 v[136:139], v140 offset:2048
	ds_read_b128 v[140:143], v140 offset:3072
	ds_read_b128 v[144:147], v156
	ds_read_b128 v[148:151], v156 offset:1024
	ds_read_b128 v[152:155], v156 offset:2048
	ds_read_b128 v[156:159], v156 offset:3072
	s_add_u32 s14, s84, 0x4000
	s_addc_u32 s15, s85, 0
	s_mov_b32 m0, s70
	v_lshl_add_u64 v[216:217], s[14:15], 0, v[200:201]
	ds_read_b128 v[160:163], v237 offset:32768
	ds_read_b128 v[164:167], v237 offset:33792
	ds_read_b128 v[168:171], v237 offset:34816
	ds_read_b128 v[172:175], v237 offset:35840
	ds_read_b128 v[176:179], v237 offset:36864
	ds_read_b128 v[180:183], v237 offset:37888
	ds_read_b128 v[184:187], v237 offset:38912
	ds_read_b128 v[188:191], v237 offset:39936
	global_load_lds_dwordx4 v[216:217], off
	v_lshl_add_u64 v[216:217], s[14:15], 0, v[202:203]
	s_mov_b32 m0, s71
	s_nop 0
	global_load_lds_dwordx4 v[216:217], off
	s_waitcnt vmcnt(8)
	s_waitcnt lgkmcnt(0)
	s_setprio 1
	s_barrier
	v_mfma_f32_16x16x32_bf16 v[124:127], v[128:131], v[160:163], v[124:127]
	v_mfma_f32_16x16x32_bf16 v[120:123], v[136:139], v[160:163], v[120:123]
	v_mfma_f32_16x16x32_bf16 v[108:111], v[128:131], v[168:171], v[108:111]
	v_mfma_f32_16x16x32_bf16 v[104:107], v[136:139], v[168:171], v[104:107]
	v_mfma_f32_16x16x32_bf16 v[92:95], v[128:131], v[176:179], v[92:95]
	v_mfma_f32_16x16x32_bf16 v[88:91], v[136:139], v[176:179], v[88:91]
	v_mfma_f32_16x16x32_bf16 v[76:79], v[128:131], v[184:187], v[76:79]
	v_mfma_f32_16x16x32_bf16 v[72:75], v[136:139], v[184:187], v[72:75]
	v_mfma_f32_16x16x32_bf16 v[124:127], v[132:135], v[164:167], v[124:127]
	v_mfma_f32_16x16x32_bf16 v[120:123], v[140:143], v[164:167], v[120:123]
	v_mfma_f32_16x16x32_bf16 v[108:111], v[132:135], v[172:175], v[108:111]
	v_mfma_f32_16x16x32_bf16 v[104:107], v[140:143], v[172:175], v[104:107]
	v_mfma_f32_16x16x32_bf16 v[92:95], v[132:135], v[180:183], v[92:95]
	v_mfma_f32_16x16x32_bf16 v[88:91], v[140:143], v[180:183], v[88:91]
	v_mfma_f32_16x16x32_bf16 v[76:79], v[132:135], v[188:191], v[76:79]
	v_mfma_f32_16x16x32_bf16 v[72:75], v[140:143], v[188:191], v[72:75]
	s_setprio 0
	s_setprio 1
	v_mfma_f32_16x16x32_bf16 v[116:119], v[144:147], v[160:163], v[116:119]
	v_mfma_f32_16x16x32_bf16 v[112:115], v[152:155], v[160:163], v[112:115]
	v_mfma_f32_16x16x32_bf16 v[100:103], v[144:147], v[168:171], v[100:103]
	v_mfma_f32_16x16x32_bf16 v[96:99], v[152:155], v[168:171], v[96:99]
	v_mfma_f32_16x16x32_bf16 v[84:87], v[144:147], v[176:179], v[84:87]
	v_mfma_f32_16x16x32_bf16 v[80:83], v[152:155], v[176:179], v[80:83]
	v_mfma_f32_16x16x32_bf16 v[68:71], v[144:147], v[184:187], v[68:71]
	v_mfma_f32_16x16x32_bf16 v[64:67], v[152:155], v[184:187], v[64:67]
	v_mfma_f32_16x16x32_bf16 v[116:119], v[148:151], v[164:167], v[116:119]
	v_mfma_f32_16x16x32_bf16 v[112:115], v[156:159], v[164:167], v[112:115]
	v_mfma_f32_16x16x32_bf16 v[100:103], v[148:151], v[172:175], v[100:103]
	v_mfma_f32_16x16x32_bf16 v[96:99], v[156:159], v[172:175], v[96:99]
	v_mfma_f32_16x16x32_bf16 v[84:87], v[148:151], v[180:183], v[84:87]
	v_mfma_f32_16x16x32_bf16 v[80:83], v[156:159], v[180:183], v[80:83]
	v_mfma_f32_16x16x32_bf16 v[68:71], v[148:151], v[188:191], v[68:71]
	v_mfma_f32_16x16x32_bf16 v[64:67], v[156:159], v[188:191], v[64:67]
	s_setprio 0
	s_barrier
; #define PG8_STAGE(bufoff, gbase, voff) do { _Pragma("unroll") for (int _i = 0; _i < 2; ++_i) \
;         __builtin_amdgcn_global_load_lds((const unsigned*)((const char*)(gbase) + (voff)[_i]), (PG8_LAS unsigned*)(lds + (bufoff) + ldsw + _i * 8192), 16, 0, 0); } while (0)
; #define PG8_LDA(dst, b, h) do { _Pragma("unroll") for (int m = 0; m < 4; ++m) _Pragma("unroll") for (int k = 0; k < 2; ++k) dst[m][k] = *(const PG8_LAS bf16x8*)(lds + PG8_SA(b, h) + aoff + m * 2048 + k * 1024); } while (0)
; #define PG8_MMA(ai, bj, At, Bt) do { __builtin_amdgcn_s_setprio(1); _Pragma("unroll") for (int m = 0; m < 4; ++m) _Pragma("unroll") for (int n = 0; n < 2; ++n) _Pragma("unroll") for (int k = 0; k < 2; ++k) \
;         acc[ai][bj][m][n] = __builtin_amdgcn_mfma_f32_16x16x32_bf16(Bt[n][k], At[m][k], acc[ai][bj][m][n], 0, 0, 0); __builtin_amdgcn_s_setprio(0); } while (0)
; #define PG8_WAIT_V(n) asm volatile("s_waitcnt vmcnt(" #n ")" ::: "memory")
; #define PG8_WAIT_L(n) asm volatile("s_waitcnt lgkmcnt(" #n ")" ::: "memory")
; #define PG8_BAR __builtin_amdgcn_s_barrier()
; #define PG8_SCHED __builtin_amdgcn_sched_barrier(0)
; template <class Epi, class Sched, bool ALIGN_EPI = false, bool SP2 = true>
; __device__ __forceinline__ void gemm_phase(PG8_LAS unsigned char* lds, const Gemm g, const Sched& S, const Epi& E) {
;     ...
;             PG8_LDA(At, 1, 1); PG8_STAGE(PG8_SB(1, 0), b3, voffB); PG8_STAGE(PG8_SB(1, 1), b3 + hstep, voffB); PG8_STAGE(PG8_SA(1, 0), a3, voffA);
;             PG8_WAIT_V(8); PG8_WAIT_L(0); PG8_BAR; PG8_MMA(1, 0, At, B0); PG8_MMA(1, 1, At, B1); PG8_BAR; PG8_SCHED;
;     ...
;         if constexpr (ALIGN_EPI) { if (wr == 0) PG8_BAR; }
	s_add_i32 s4, s4, s57
	v_lshl_add_u64 v[212:213], v[212:213], 0, s[18:19]
	s_mov_b32 m0, s4
	ds_read_b128 v[160:163], v237 offset:49152
	ds_read_b128 v[164:167], v237 offset:50176
	ds_read_b128 v[168:171], v237 offset:51200
	ds_read_b128 v[172:175], v237 offset:52224
	ds_read_b128 v[176:179], v237 offset:53248
	ds_read_b128 v[180:183], v237 offset:54272
	ds_read_b128 v[184:187], v237 offset:55296
	ds_read_b128 v[188:191], v237 offset:56320
	global_load_lds_dwordx4 v[212:213], off
	s_add_i32 m0, s4, 0x2000
	s_add_u32 s14, vcc_lo, 0xb0080
	v_lshl_add_u64 v[212:213], v[214:215], 0, s[18:19]
	s_addc_u32 s15, vcc_hi, 0
	s_add_i32 s4, s5, s57
	global_load_lds_dwordx4 v[212:213], off
	v_lshl_add_u64 v[212:213], s[14:15], 0, v[194:195]
	s_mov_b32 m0, s4
	s_nop 0
	global_load_lds_dwordx4 v[212:213], off
	v_lshl_add_u64 v[212:213], s[14:15], 0, v[204:205]
	s_add_i32 m0, s4, 0x2000
	s_nop 0
	global_load_lds_dwordx4 v[212:213], off
	v_lshl_add_u64 v[212:213], s[46:47], 0, v[200:201]
	s_mov_b32 m0, s34
	s_nop 0
	global_load_lds_dwordx4 v[212:213], off
	v_lshl_add_u64 v[212:213], s[46:47], 0, v[202:203]
	s_mov_b32 m0, s35
	s_nop 0
	global_load_lds_dwordx4 v[212:213], off
	s_waitcnt vmcnt(8)
	s_waitcnt lgkmcnt(0)
	s_setprio 1
	s_barrier
	v_mfma_f32_16x16x32_bf16 v[60:63], v[128:131], v[160:163], v[60:63]
	v_mfma_f32_16x16x32_bf16 v[56:59], v[136:139], v[160:163], v[56:59]
	v_mfma_f32_16x16x32_bf16 v[44:47], v[128:131], v[168:171], v[44:47]
	v_mfma_f32_16x16x32_bf16 v[40:43], v[136:139], v[168:171], v[40:43]
	v_mfma_f32_16x16x32_bf16 v[28:31], v[128:131], v[176:179], v[28:31]
	v_mfma_f32_16x16x32_bf16 v[24:27], v[136:139], v[176:179], v[24:27]
	v_mfma_f32_16x16x32_bf16 v[12:15], v[128:131], v[184:187], v[12:15]
	v_mfma_f32_16x16x32_bf16 v[8:11], v[136:139], v[184:187], v[8:11]
	v_mfma_f32_16x16x32_bf16 v[60:63], v[132:135], v[164:167], v[60:63]
	v_mfma_f32_16x16x32_bf16 v[56:59], v[140:143], v[164:167], v[56:59]
	v_mfma_f32_16x16x32_bf16 v[44:47], v[132:135], v[172:175], v[44:47]
	v_mfma_f32_16x16x32_bf16 v[40:43], v[140:143], v[172:175], v[40:43]
	v_mfma_f32_16x16x32_bf16 v[28:31], v[132:135], v[180:183], v[28:31]
	v_mfma_f32_16x16x32_bf16 v[24:27], v[140:143], v[180:183], v[24:27]
	v_mfma_f32_16x16x32_bf16 v[12:15], v[132:135], v[188:191], v[12:15]
	v_mfma_f32_16x16x32_bf16 v[8:11], v[140:143], v[188:191], v[8:11]
	s_setprio 0
	s_setprio 1
	v_mfma_f32_16x16x32_bf16 v[52:55], v[144:147], v[160:163], v[52:55]
	v_mfma_f32_16x16x32_bf16 v[48:51], v[152:155], v[160:163], v[48:51]
	v_mfma_f32_16x16x32_bf16 v[36:39], v[144:147], v[168:171], v[36:39]
	v_mfma_f32_16x16x32_bf16 v[32:35], v[152:155], v[168:171], v[32:35]
	v_mfma_f32_16x16x32_bf16 v[20:23], v[144:147], v[176:179], v[20:23]
	v_mfma_f32_16x16x32_bf16 v[16:19], v[152:155], v[176:179], v[16:19]
	v_mfma_f32_16x16x32_bf16 v[4:7], v[144:147], v[184:187], v[4:7]
	v_mfma_f32_16x16x32_bf16 v[0:3], v[152:155], v[184:187], v[0:3]
	v_mfma_f32_16x16x32_bf16 v[52:55], v[148:151], v[164:167], v[52:55]
	v_mfma_f32_16x16x32_bf16 v[48:51], v[156:159], v[164:167], v[48:51]
	v_mfma_f32_16x16x32_bf16 v[36:39], v[148:151], v[172:175], v[36:39]
	v_mfma_f32_16x16x32_bf16 v[32:35], v[156:159], v[172:175], v[32:35]
	v_mfma_f32_16x16x32_bf16 v[20:23], v[148:151], v[180:183], v[20:23]
	v_mfma_f32_16x16x32_bf16 v[16:19], v[156:159], v[180:183], v[16:19]
	v_mfma_f32_16x16x32_bf16 v[4:7], v[148:151], v[188:191], v[4:7]
	v_mfma_f32_16x16x32_bf16 v[0:3], v[156:159], v[188:191], v[0:3]
	s_setprio 0
	s_barrier
	s_add_i32 s7, s7, 2
	s_add_u32 s42, s42, 0x10000
	s_addc_u32 s43, s43, 0
	s_add_u32 s17, s17, 0x100
	s_addc_u32 s6, s6, 0
	s_cmp_gt_u32 s7, 41
	s_cbranch_scc0 .LBB0_236
	s_and_b64 vcc, exec, s[48:49]
	s_cbranch_vccz .LBB0_239
	s_barrier

; #define PG8_STAGE(bufoff, gbase, voff) do { _Pragma("unroll") for (int _i = 0; _i < 2; ++_i) \
;         __builtin_amdgcn_global_load_lds((const unsigned*)((const char*)(gbase) + (voff)[_i]), (PG8_LAS unsigned*)(lds + (bufoff) + ldsw + _i * 8192), 16, 0, 0); } while (0)
; #define PG8_LDA(dst, b, h) do { _Pragma("unroll") for (int m = 0; m < 4; ++m) _Pragma("unroll") for (int k = 0; k < 2; ++k) dst[m][k] = *(const PG8_LAS bf16x8*)(lds + PG8_SA(b, h) + aoff + m * 2048 + k * 1024); } while (0)
; #define PG8_LDB(dst, b, h) do { _Pragma("unroll") for (int n = 0; n < 2; ++n) _Pragma("unroll") for (int k = 0; k < 2; ++k) dst[n][k] = *(const PG8_LAS bf16x8*)(lds + PG8_SB(b, h) + boff + n * 2048 + k * 1024); } while (0)
; #define PG8_WAIT_V(n) asm volatile("s_waitcnt vmcnt(" #n ")" ::: "memory")
; #define PG8_WAIT_L(n) asm volatile("s_waitcnt lgkmcnt(" #n ")" ::: "memory")
; #define PG8_BAR __builtin_amdgcn_s_barrier()
; #define PG8_SCHED __builtin_amdgcn_sched_barrier(0)
; template <class Epi, class Sched, bool ALIGN_EPI = false, bool SP2 = true>
; __device__ __forceinline__ void gemm_phase(PG8_LAS unsigned char* lds, const Gemm g, const Sched& S, const Epi& E) {
;     ...
;         const bool has_next = S.next(ui + 1, nxt);
;         const char* nA = has_next ? (const char*)g.A + (size_t)nxt.pm * tstepA + (size_t)nxt.pn * pnA : cA; const char* nB = has_next ? (const char*)g.Bt + (size_t)nxt.pn * tstep : cB;
;         for (int t = 0; t < nt; t += 2) {
;             const bool last = (t == nt - 2);
;             const char* a1 = cA + (size_t)(t + 1) * kstepA;
;             const char* a2 = last ? nA : cA + (size_t)(t + 2) * kstepA; const char* b2 = last ? nB : cB + (size_t)(t + 2) * kstep;
;             const char* a3 = a2 + kstepA; const char* b3 = b2 + kstep;
;             if (last && has_next) S.a_ready(nxt);
;             if constexpr (SP2) {
;             PG8_LDB(B0, 0, 0); PG8_LDB(B1, 0, 1); PG8_SCHED; PG8_LDA(At, 0, 0); PG8_STAGE(PG8_SA(1, 1), a1 + hstepA, voffA);
;             PG8_WAIT_V(8); PG8_WAIT_L(0); PG8_BAR; PG8_MMA(0, 0, At, B0); PG8_MMA(0, 1, At, B1); PG8_BAR; PG8_SCHED;
;     ...
;         for (int a = 0; a < 2; ++a)
; #pragma unroll
;             for (int b = 0; b < 2; ++b)
; #pragma unroll
;                 for (int m = 0; m < 4; ++m)
; #pragma unroll
;                     for (int n = 0; n < 2; ++n) acc[a][b][m][n] = (f32x4){0.f, 0.f, 0.f, 0.f};
.LBB0_375:
	s_ashr_i32 s41, s40, 31
	s_lshl_b64 s[6:7], s[40:41], 19
	s_add_u32 s42, s54, s6
	s_addc_u32 s43, s55, s7
	s_and_b64 s[6:7], s[36:37], exec
	s_cselect_b32 s16, s43, s53
	s_cselect_b32 s17, s42, s52
	s_ashr_i32 s39, s38, 31
	s_lshl_b64 s[6:7], s[38:39], 19
	s_add_u32 s44, s10, s6
	s_addc_u32 s45, s11, s7
	s_and_b64 s[6:7], s[36:37], exec
	s_cselect_b32 s39, s45, s47
	s_cselect_b32 s41, s44, s46
	s_add_u32 s52, s52, 0x40080
	s_addc_u32 s53, s53, 0
	s_add_u32 s6, s46, 0x100
	s_addc_u32 s7, s47, 0
	s_mov_b32 s59, -2
	s_add_u32 s4, s52, 0xfffc0080
	s_addc_u32 s5, s53, -1
	s_add_i32 s14, 0, 0x10000
	s_cmp_eq_u32 s59, 12
	s_cselect_b32 s85, s16, s5
	s_cselect_b32 s84, s17, s4
	v_add_u32_e32 v138, s14, v145
	s_cselect_b32 s47, s39, s7
	s_cselect_b32 s46, s41, s6
	s_add_i32 s4, 0, 0x14000
	ds_read_b128 v[150:153], v138
	ds_read_b128 v[154:157], v138 offset:1024
	ds_read_b128 v[158:161], v138 offset:2048
	ds_read_b128 v[162:165], v138 offset:3072
	v_add_u32_e32 v138, s4, v145
	ds_read_b128 v[166:169], v138
	ds_read_b128 v[170:173], v138 offset:1024
	ds_read_b128 v[174:177], v138 offset:2048
	ds_read_b128 v[178:181], v138 offset:3072
	v_lshl_add_u64 v[138:139], s[52:53], 0, v[134:135]
	s_add_i32 m0, s31, 0xc000
	ds_read_b128 v[182:185], v149
	ds_read_b128 v[186:189], v149 offset:1024
	ds_read_b128 v[200:203], v149 offset:2048
	ds_read_b128 v[204:207], v149 offset:3072
	ds_read_b128 v[208:211], v149 offset:4096
	ds_read_b128 v[212:215], v149 offset:5120
	ds_read_b128 v[216:219], v149 offset:6144
	ds_read_b128 v[220:223], v149 offset:7168
	global_load_lds_dwordx4 v[138:139], off
	v_lshl_add_u64 v[138:139], s[52:53], 0, v[136:137]
	s_add_i32 m0, s31, 0xe000
	s_nop 0
	global_load_lds_dwordx4 v[138:139], off
	s_waitcnt vmcnt(8)
	s_waitcnt lgkmcnt(0)
	s_setprio 1
	s_barrier
	v_mfma_f32_16x16x32_bf16 v[124:127], v[150:153], v[182:185], 0
	v_mfma_f32_16x16x32_bf16 v[120:123], v[158:161], v[182:185], 0
	v_mfma_f32_16x16x32_bf16 v[112:115], v[150:153], v[200:203], 0
	v_mfma_f32_16x16x32_bf16 v[104:107], v[158:161], v[200:203], 0
	v_mfma_f32_16x16x32_bf16 v[96:99], v[150:153], v[208:211], 0
	v_mfma_f32_16x16x32_bf16 v[88:91], v[158:161], v[208:211], 0
	v_mfma_f32_16x16x32_bf16 v[80:83], v[150:153], v[216:219], 0
	v_mfma_f32_16x16x32_bf16 v[72:75], v[158:161], v[216:219], 0
	v_mfma_f32_16x16x32_bf16 v[124:127], v[154:157], v[186:189], v[124:127]
	v_mfma_f32_16x16x32_bf16 v[120:123], v[162:165], v[186:189], v[120:123]
	v_mfma_f32_16x16x32_bf16 v[112:115], v[154:157], v[204:207], v[112:115]
	v_mfma_f32_16x16x32_bf16 v[104:107], v[162:165], v[204:207], v[104:107]
	v_mfma_f32_16x16x32_bf16 v[96:99], v[154:157], v[212:215], v[96:99]
	v_mfma_f32_16x16x32_bf16 v[88:91], v[162:165], v[212:215], v[88:91]
	v_mfma_f32_16x16x32_bf16 v[80:83], v[154:157], v[220:223], v[80:83]
	v_mfma_f32_16x16x32_bf16 v[72:75], v[162:165], v[220:223], v[72:75]
	s_setprio 0
	s_setprio 1
	v_mfma_f32_16x16x32_bf16 v[116:119], v[166:169], v[182:185], 0
	v_mfma_f32_16x16x32_bf16 v[108:111], v[174:177], v[182:185], 0
	v_mfma_f32_16x16x32_bf16 v[100:103], v[166:169], v[200:203], 0
	v_mfma_f32_16x16x32_bf16 v[92:95], v[174:177], v[200:203], 0
	v_mfma_f32_16x16x32_bf16 v[84:87], v[166:169], v[208:211], 0
	v_mfma_f32_16x16x32_bf16 v[76:79], v[174:177], v[208:211], 0
	v_mfma_f32_16x16x32_bf16 v[68:71], v[166:169], v[216:219], 0
	v_mfma_f32_16x16x32_bf16 v[64:67], v[174:177], v[216:219], 0
	v_mfma_f32_16x16x32_bf16 v[116:119], v[170:173], v[186:189], v[116:119]
	v_mfma_f32_16x16x32_bf16 v[108:111], v[178:181], v[186:189], v[108:111]
	v_mfma_f32_16x16x32_bf16 v[100:103], v[170:173], v[204:207], v[100:103]
	v_mfma_f32_16x16x32_bf16 v[92:95], v[178:181], v[204:207], v[92:95]
	v_mfma_f32_16x16x32_bf16 v[84:87], v[170:173], v[212:215], v[84:87]
	v_mfma_f32_16x16x32_bf16 v[76:79], v[178:181], v[212:215], v[76:79]
	v_mfma_f32_16x16x32_bf16 v[68:71], v[170:173], v[220:223], v[68:71]
	v_mfma_f32_16x16x32_bf16 v[64:67], v[178:181], v[220:223], v[64:67]
	s_setprio 0
	s_barrier
; #define PG8_STAGE(bufoff, gbase, voff) do { _Pragma("unroll") for (int _i = 0; _i < 2; ++_i) \
;         __builtin_amdgcn_global_load_lds((const unsigned*)((const char*)(gbase) + (voff)[_i]), (PG8_LAS unsigned*)(lds + (bufoff) + ldsw + _i * 8192), 16, 0, 0); } while (0)
; #define PG8_LDA(dst, b, h) do { _Pragma("unroll") for (int m = 0; m < 4; ++m) _Pragma("unroll") for (int k = 0; k < 2; ++k) dst[m][k] = *(const PG8_LAS bf16x8*)(lds + PG8_SA(b, h) + aoff + m * 2048 + k * 1024); } while (0)
; #define PG8_MMA(ai, bj, At, Bt) do { __builtin_amdgcn_s_setprio(1); _Pragma("unroll") for (int m = 0; m < 4; ++m) _Pragma("unroll") for (int n = 0; n < 2; ++n) _Pragma("unroll") for (int k = 0; k < 2; ++k) \
;         acc[ai][bj][m][n] = __builtin_amdgcn_mfma_f32_16x16x32_bf16(Bt[n][k], At[m][k], acc[ai][bj][m][n], 0, 0, 0); __builtin_amdgcn_s_setprio(0); } while (0)
; #define PG8_WAIT_V(n) asm volatile("s_waitcnt vmcnt(" #n ")" ::: "memory")
; #define PG8_WAIT_L(n) asm volatile("s_waitcnt lgkmcnt(" #n ")" ::: "memory")
; #define PG8_BAR __builtin_amdgcn_s_barrier()
; #define PG8_SCHED __builtin_amdgcn_sched_barrier(0)
; template <class Epi, class Sched, bool ALIGN_EPI = false, bool SP2 = true>
; __device__ __forceinline__ void gemm_phase(PG8_LAS unsigned char* lds, const Gemm g, const Sched& S, const Epi& E) {
;     ...
;             PG8_LDA(At, 0, 1); PG8_STAGE(PG8_SB(0, 0), b2, voffB); PG8_STAGE(PG8_SB(0, 1), b2 + hstep, voffB); PG8_STAGE(PG8_SA(0, 0), a2, voffA);
;             PG8_WAIT_V(8); PG8_WAIT_L(0); PG8_BAR; PG8_MMA(1, 0, At, B0); PG8_MMA(1, 1, At, B1); PG8_BAR; PG8_SCHED;
	s_add_i32 s5, s14, s28
	v_lshl_add_u64 v[138:139], s[46:47], 0, v[194:195]
	s_mov_b32 m0, s5
	ds_read_b128 v[182:185], v149 offset:16384
	ds_read_b128 v[186:189], v149 offset:17408
	ds_read_b128 v[200:203], v149 offset:18432
	ds_read_b128 v[204:207], v149 offset:19456
	ds_read_b128 v[208:211], v149 offset:20480
	ds_read_b128 v[212:215], v149 offset:21504
	ds_read_b128 v[216:219], v149 offset:22528
	ds_read_b128 v[220:223], v149 offset:23552
	global_load_lds_dwordx4 v[138:139], off
	s_add_i32 m0, s5, 0x2000
	s_add_u32 s14, s46, 0x40000
	v_lshl_add_u64 v[142:143], s[46:47], 0, v[128:129]
	s_addc_u32 s15, s47, 0
	s_add_i32 s4, s4, s28
	global_load_lds_dwordx4 v[142:143], off
	v_lshl_add_u64 v[190:191], s[14:15], 0, v[194:195]
	s_mov_b32 m0, s4
	v_lshl_add_u64 v[224:225], s[84:85], 0, v[130:131]
	global_load_lds_dwordx4 v[190:191], off
	v_lshl_add_u64 v[190:191], s[14:15], 0, v[128:129]
	s_add_i32 m0, s4, 0x2000
	s_nop 0
	global_load_lds_dwordx4 v[190:191], off
	v_lshl_add_u64 v[190:191], s[84:85], 0, v[132:133]
	s_mov_b32 m0, s31
	s_nop 0
	global_load_lds_dwordx4 v[190:191], off
	s_mov_b32 m0, s34
	s_nop 0
	global_load_lds_dwordx4 v[224:225], off
	s_waitcnt vmcnt(8)
	s_waitcnt lgkmcnt(0)
	s_setprio 1
	s_barrier
	v_mfma_f32_16x16x32_bf16 v[60:63], v[150:153], v[182:185], 0
	v_mfma_f32_16x16x32_bf16 v[56:59], v[158:161], v[182:185], 0
	v_mfma_f32_16x16x32_bf16 v[48:51], v[150:153], v[200:203], 0
	v_mfma_f32_16x16x32_bf16 v[40:43], v[158:161], v[200:203], 0
	v_mfma_f32_16x16x32_bf16 v[32:35], v[150:153], v[208:211], 0
	v_mfma_f32_16x16x32_bf16 v[24:27], v[158:161], v[208:211], 0
	v_mfma_f32_16x16x32_bf16 v[16:19], v[150:153], v[216:219], 0
	v_mfma_f32_16x16x32_bf16 v[8:11], v[158:161], v[216:219], 0
	v_mfma_f32_16x16x32_bf16 v[60:63], v[154:157], v[186:189], v[60:63]
	v_mfma_f32_16x16x32_bf16 v[56:59], v[162:165], v[186:189], v[56:59]
	v_mfma_f32_16x16x32_bf16 v[48:51], v[154:157], v[204:207], v[48:51]
	v_mfma_f32_16x16x32_bf16 v[40:43], v[162:165], v[204:207], v[40:43]
	v_mfma_f32_16x16x32_bf16 v[32:35], v[154:157], v[212:215], v[32:35]
	v_mfma_f32_16x16x32_bf16 v[24:27], v[162:165], v[212:215], v[24:27]
	v_mfma_f32_16x16x32_bf16 v[16:19], v[154:157], v[220:223], v[16:19]
	v_mfma_f32_16x16x32_bf16 v[8:11], v[162:165], v[220:223], v[8:11]
	s_setprio 0
	s_setprio 1
	v_mfma_f32_16x16x32_bf16 v[52:55], v[166:169], v[182:185], 0
	v_mfma_f32_16x16x32_bf16 v[44:47], v[174:177], v[182:185], 0
	v_mfma_f32_16x16x32_bf16 v[36:39], v[166:169], v[200:203], 0
	v_mfma_f32_16x16x32_bf16 v[28:31], v[174:177], v[200:203], 0
	v_mfma_f32_16x16x32_bf16 v[20:23], v[166:169], v[208:211], 0
	v_mfma_f32_16x16x32_bf16 v[12:15], v[174:177], v[208:211], 0
	v_mfma_f32_16x16x32_bf16 v[4:7], v[166:169], v[216:219], 0
	v_mfma_f32_16x16x32_bf16 v[0:3], v[174:177], v[216:219], 0
	v_mfma_f32_16x16x32_bf16 v[52:55], v[170:173], v[186:189], v[52:55]
	v_mfma_f32_16x16x32_bf16 v[44:47], v[178:181], v[186:189], v[44:47]
	v_mfma_f32_16x16x32_bf16 v[36:39], v[170:173], v[204:207], v[36:39]
	v_mfma_f32_16x16x32_bf16 v[28:31], v[178:181], v[204:207], v[28:31]
	v_mfma_f32_16x16x32_bf16 v[20:23], v[170:173], v[212:215], v[20:23]
	v_mfma_f32_16x16x32_bf16 v[12:15], v[178:181], v[212:215], v[12:15]
	v_mfma_f32_16x16x32_bf16 v[4:7], v[170:173], v[220:223], v[4:7]
	v_mfma_f32_16x16x32_bf16 v[0:3], v[178:181], v[220:223], v[0:3]
	s_setprio 0
	s_barrier
	s_branch .Lmi_s3

; #define PG8_STAGE(bufoff, gbase, voff) do { _Pragma("unroll") for (int _i = 0; _i < 2; ++_i) \
;         __builtin_amdgcn_global_load_lds((const unsigned*)((const char*)(gbase) + (voff)[_i]), (PG8_LAS unsigned*)(lds + (bufoff) + ldsw + _i * 8192), 16, 0, 0); } while (0)
; #define PG8_LDA(dst, b, h) do { _Pragma("unroll") for (int m = 0; m < 4; ++m) _Pragma("unroll") for (int k = 0; k < 2; ++k) dst[m][k] = *(const PG8_LAS bf16x8*)(lds + PG8_SA(b, h) + aoff + m * 2048 + k * 1024); } while (0)
; #define PG8_LDB(dst, b, h) do { _Pragma("unroll") for (int n = 0; n < 2; ++n) _Pragma("unroll") for (int k = 0; k < 2; ++k) dst[n][k] = *(const PG8_LAS bf16x8*)(lds + PG8_SB(b, h) + boff + n * 2048 + k * 1024); } while (0)
; #define PG8_MMA(ai, bj, At, Bt) do { __builtin_amdgcn_s_setprio(1); _Pragma("unroll") for (int m = 0; m < 4; ++m) _Pragma("unroll") for (int n = 0; n < 2; ++n) _Pragma("unroll") for (int k = 0; k < 2; ++k) \
;         acc[ai][bj][m][n] = __builtin_amdgcn_mfma_f32_16x16x32_bf16(Bt[n][k], At[m][k], acc[ai][bj][m][n], 0, 0, 0); __builtin_amdgcn_s_setprio(0); } while (0)
; #define PG8_WAIT_V(n) asm volatile("s_waitcnt vmcnt(" #n ")" ::: "memory")
; #define PG8_WAIT_L(n) asm volatile("s_waitcnt lgkmcnt(" #n ")" ::: "memory")
; #define PG8_BAR __builtin_amdgcn_s_barrier()
; #define PG8_SCHED __builtin_amdgcn_sched_barrier(0)
; template <class Epi, class Sched, bool ALIGN_EPI = false, bool SP2 = true>
; __device__ __forceinline__ void gemm_phase(PG8_LAS unsigned char* lds, const Gemm g, const Sched& S, const Epi& E) {
;     ...
;             PG8_LDB(B0, 1, 0); PG8_LDB(B1, 1, 1); PG8_SCHED; PG8_LDA(At, 1, 0); PG8_STAGE(PG8_SA(0, 1), a2 + hstepA, voffA);
;             PG8_WAIT_V(8); PG8_WAIT_L(0); PG8_BAR; PG8_MMA(0, 0, At, B0); PG8_MMA(0, 1, At, B1); PG8_BAR; PG8_SCHED;
.Lmi_s3:
	s_add_i32 s4, 0, 0x18000
	v_add_u32_e32 v140, s4, v145
	s_add_i32 s5, 0, 0x1c000
	ds_read_b128 v[150:153], v140
	ds_read_b128 v[154:157], v140 offset:1024
	ds_read_b128 v[158:161], v140 offset:2048
	ds_read_b128 v[162:165], v140 offset:3072
	v_add_u32_e32 v140, s5, v145
	ds_read_b128 v[166:169], v140
	ds_read_b128 v[170:173], v140 offset:1024
	ds_read_b128 v[174:177], v140 offset:2048
	ds_read_b128 v[178:181], v140 offset:3072
	s_add_u32 s14, s84, 0x40000
	s_addc_u32 s15, s85, 0
	s_mov_b32 m0, s35
	v_lshl_add_u64 v[226:227], s[14:15], 0, v[132:133]
	ds_read_b128 v[182:185], v149 offset:32768
	ds_read_b128 v[186:189], v149 offset:33792
	ds_read_b128 v[200:203], v149 offset:34816
	ds_read_b128 v[204:207], v149 offset:35840
	ds_read_b128 v[208:211], v149 offset:36864
	ds_read_b128 v[212:215], v149 offset:37888
	ds_read_b128 v[216:219], v149 offset:38912
	ds_read_b128 v[220:223], v149 offset:39936
	global_load_lds_dwordx4 v[226:227], off
	v_lshl_add_u64 v[226:227], s[14:15], 0, v[130:131]
	s_mov_b32 m0, s49
	s_nop 0
	global_load_lds_dwordx4 v[226:227], off
	s_waitcnt vmcnt(8)
	s_waitcnt lgkmcnt(0)
	s_setprio 1
	s_barrier
	v_mfma_f32_16x16x32_bf16 v[124:127], v[150:153], v[182:185], v[124:127]
	v_mfma_f32_16x16x32_bf16 v[120:123], v[158:161], v[182:185], v[120:123]
	v_mfma_f32_16x16x32_bf16 v[112:115], v[150:153], v[200:203], v[112:115]
	v_mfma_f32_16x16x32_bf16 v[104:107], v[158:161], v[200:203], v[104:107]
	v_mfma_f32_16x16x32_bf16 v[96:99], v[150:153], v[208:211], v[96:99]
	v_mfma_f32_16x16x32_bf16 v[88:91], v[158:161], v[208:211], v[88:91]
	v_mfma_f32_16x16x32_bf16 v[80:83], v[150:153], v[216:219], v[80:83]
	v_mfma_f32_16x16x32_bf16 v[72:75], v[158:161], v[216:219], v[72:75]
	v_mfma_f32_16x16x32_bf16 v[124:127], v[154:157], v[186:189], v[124:127]
	v_mfma_f32_16x16x32_bf16 v[120:123], v[162:165], v[186:189], v[120:123]
	v_mfma_f32_16x16x32_bf16 v[112:115], v[154:157], v[204:207], v[112:115]
	v_mfma_f32_16x16x32_bf16 v[104:107], v[162:165], v[204:207], v[104:107]
	v_mfma_f32_16x16x32_bf16 v[96:99], v[154:157], v[212:215], v[96:99]
	v_mfma_f32_16x16x32_bf16 v[88:91], v[162:165], v[212:215], v[88:91]
	v_mfma_f32_16x16x32_bf16 v[80:83], v[154:157], v[220:223], v[80:83]
	v_mfma_f32_16x16x32_bf16 v[72:75], v[162:165], v[220:223], v[72:75]
	s_setprio 0
	s_setprio 1
	v_mfma_f32_16x16x32_bf16 v[116:119], v[166:169], v[182:185], v[116:119]
	v_mfma_f32_16x16x32_bf16 v[108:111], v[174:177], v[182:185], v[108:111]
	v_mfma_f32_16x16x32_bf16 v[100:103], v[166:169], v[200:203], v[100:103]
	v_mfma_f32_16x16x32_bf16 v[92:95], v[174:177], v[200:203], v[92:95]
	v_mfma_f32_16x16x32_bf16 v[84:87], v[166:169], v[208:211], v[84:87]
	v_mfma_f32_16x16x32_bf16 v[76:79], v[174:177], v[208:211], v[76:79]
	v_mfma_f32_16x16x32_bf16 v[68:71], v[166:169], v[216:219], v[68:71]
	v_mfma_f32_16x16x32_bf16 v[64:67], v[174:177], v[216:219], v[64:67]
	v_mfma_f32_16x16x32_bf16 v[116:119], v[170:173], v[186:189], v[116:119]
	v_mfma_f32_16x16x32_bf16 v[108:111], v[178:181], v[186:189], v[108:111]
	v_mfma_f32_16x16x32_bf16 v[100:103], v[170:173], v[204:207], v[100:103]
	v_mfma_f32_16x16x32_bf16 v[92:95], v[178:181], v[204:207], v[92:95]
	v_mfma_f32_16x16x32_bf16 v[84:87], v[170:173], v[212:215], v[84:87]
	v_mfma_f32_16x16x32_bf16 v[76:79], v[178:181], v[212:215], v[76:79]
	v_mfma_f32_16x16x32_bf16 v[68:71], v[170:173], v[220:223], v[68:71]
	v_mfma_f32_16x16x32_bf16 v[64:67], v[178:181], v[220:223], v[64:67]
	s_setprio 0
	s_barrier
; #define PG8_STAGE(bufoff, gbase, voff) do { _Pragma("unroll") for (int _i = 0; _i < 2; ++_i) \
;         __builtin_amdgcn_global_load_lds((const unsigned*)((const char*)(gbase) + (voff)[_i]), (PG8_LAS unsigned*)(lds + (bufoff) + ldsw + _i * 8192), 16, 0, 0); } while (0)
; #define PG8_LDA(dst, b, h) do { _Pragma("unroll") for (int m = 0; m < 4; ++m) _Pragma("unroll") for (int k = 0; k < 2; ++k) dst[m][k] = *(const PG8_LAS bf16x8*)(lds + PG8_SA(b, h) + aoff + m * 2048 + k * 1024); } while (0)
; #define PG8_MMA(ai, bj, At, Bt) do { __builtin_amdgcn_s_setprio(1); _Pragma("unroll") for (int m = 0; m < 4; ++m) _Pragma("unroll") for (int n = 0; n < 2; ++n) _Pragma("unroll") for (int k = 0; k < 2; ++k) \
;         acc[ai][bj][m][n] = __builtin_amdgcn_mfma_f32_16x16x32_bf16(Bt[n][k], At[m][k], acc[ai][bj][m][n], 0, 0, 0); __builtin_amdgcn_s_setprio(0); } while (0)
; #define PG8_WAIT_V(n) asm volatile("s_waitcnt vmcnt(" #n ")" ::: "memory")
; #define PG8_WAIT_L(n) asm volatile("s_waitcnt lgkmcnt(" #n ")" ::: "memory")
; #define PG8_BAR __builtin_amdgcn_s_barrier()
; #define PG8_SCHED __builtin_amdgcn_sched_barrier(0)
; template <class Epi, class Sched, bool ALIGN_EPI = false, bool SP2 = true>
; __device__ __forceinline__ void gemm_phase(PG8_LAS unsigned char* lds, const Gemm g, const Sched& S, const Epi& E) {
;     ...
;             PG8_LDA(At, 1, 1); PG8_STAGE(PG8_SB(1, 0), b3, voffB); PG8_STAGE(PG8_SB(1, 1), b3 + hstep, voffB); PG8_STAGE(PG8_SA(1, 0), a3, voffA);
;             PG8_WAIT_V(8); PG8_WAIT_L(0); PG8_BAR; PG8_MMA(1, 0, At, B0); PG8_MMA(1, 1, At, B1); PG8_BAR; PG8_SCHED;
;     ...
;         if constexpr (ALIGN_EPI) { if (wr == 0) PG8_BAR; }
	s_add_i32 s4, s4, s28
	v_lshl_add_u64 v[138:139], v[138:139], 0, s[18:19]
	s_mov_b32 m0, s4
	ds_read_b128 v[182:185], v149 offset:49152
	ds_read_b128 v[186:189], v149 offset:50176
	ds_read_b128 v[200:203], v149 offset:51200
	ds_read_b128 v[204:207], v149 offset:52224
	ds_read_b128 v[208:211], v149 offset:53248
	ds_read_b128 v[212:215], v149 offset:54272
	ds_read_b128 v[216:219], v149 offset:55296
	ds_read_b128 v[220:223], v149 offset:56320
	global_load_lds_dwordx4 v[138:139], off
	s_add_i32 m0, s4, 0x2000
	s_add_u32 s14, s46, 0x40080
	v_lshl_add_u64 v[138:139], v[142:143], 0, s[18:19]
	s_addc_u32 s15, s47, 0
	s_add_i32 s4, s5, s28
	global_load_lds_dwordx4 v[138:139], off
	v_lshl_add_u64 v[138:139], s[14:15], 0, v[194:195]
	s_mov_b32 m0, s4
	s_nop 0
	global_load_lds_dwordx4 v[138:139], off
	v_lshl_add_u64 v[138:139], s[14:15], 0, v[128:129]
	s_add_i32 m0, s4, 0x2000
	s_nop 0
	global_load_lds_dwordx4 v[138:139], off
	v_lshl_add_u64 v[138:139], v[190:191], 0, s[18:19]
	s_mov_b32 m0, s51
	s_nop 0
	global_load_lds_dwordx4 v[138:139], off
	v_lshl_add_u64 v[138:139], v[224:225], 0, s[18:19]
	s_mov_b32 m0, s57
	s_nop 0
	global_load_lds_dwordx4 v[138:139], off
	s_waitcnt vmcnt(8)
	s_waitcnt lgkmcnt(0)
	s_setprio 1
	s_barrier
	v_mfma_f32_16x16x32_bf16 v[60:63], v[150:153], v[182:185], v[60:63]
	v_mfma_f32_16x16x32_bf16 v[56:59], v[158:161], v[182:185], v[56:59]
	v_mfma_f32_16x16x32_bf16 v[48:51], v[150:153], v[200:203], v[48:51]
	v_mfma_f32_16x16x32_bf16 v[40:43], v[158:161], v[200:203], v[40:43]
	v_mfma_f32_16x16x32_bf16 v[32:35], v[150:153], v[208:211], v[32:35]
	v_mfma_f32_16x16x32_bf16 v[24:27], v[158:161], v[208:211], v[24:27]
	v_mfma_f32_16x16x32_bf16 v[16:19], v[150:153], v[216:219], v[16:19]
	v_mfma_f32_16x16x32_bf16 v[8:11], v[158:161], v[216:219], v[8:11]
	v_mfma_f32_16x16x32_bf16 v[60:63], v[154:157], v[186:189], v[60:63]
	v_mfma_f32_16x16x32_bf16 v[56:59], v[162:165], v[186:189], v[56:59]
	v_mfma_f32_16x16x32_bf16 v[48:51], v[154:157], v[204:207], v[48:51]
	v_mfma_f32_16x16x32_bf16 v[40:43], v[162:165], v[204:207], v[40:43]
	v_mfma_f32_16x16x32_bf16 v[32:35], v[154:157], v[212:215], v[32:35]
	v_mfma_f32_16x16x32_bf16 v[24:27], v[162:165], v[212:215], v[24:27]
	v_mfma_f32_16x16x32_bf16 v[16:19], v[154:157], v[220:223], v[16:19]
	v_mfma_f32_16x16x32_bf16 v[8:11], v[162:165], v[220:223], v[8:11]
	s_setprio 0
	s_setprio 1
	v_mfma_f32_16x16x32_bf16 v[52:55], v[166:169], v[182:185], v[52:55]
	v_mfma_f32_16x16x32_bf16 v[44:47], v[174:177], v[182:185], v[44:47]
	v_mfma_f32_16x16x32_bf16 v[36:39], v[166:169], v[200:203], v[36:39]
	v_mfma_f32_16x16x32_bf16 v[28:31], v[174:177], v[200:203], v[28:31]
	v_mfma_f32_16x16x32_bf16 v[20:23], v[166:169], v[208:211], v[20:23]
	v_mfma_f32_16x16x32_bf16 v[12:15], v[174:177], v[208:211], v[12:15]
	v_mfma_f32_16x16x32_bf16 v[4:7], v[166:169], v[216:219], v[4:7]
	v_mfma_f32_16x16x32_bf16 v[0:3], v[174:177], v[216:219], v[0:3]
	v_mfma_f32_16x16x32_bf16 v[52:55], v[170:173], v[186:189], v[52:55]
	v_mfma_f32_16x16x32_bf16 v[44:47], v[178:181], v[186:189], v[44:47]
	v_mfma_f32_16x16x32_bf16 v[36:39], v[170:173], v[204:207], v[36:39]
	v_mfma_f32_16x16x32_bf16 v[28:31], v[178:181], v[204:207], v[28:31]
	v_mfma_f32_16x16x32_bf16 v[20:23], v[170:173], v[212:215], v[20:23]
	v_mfma_f32_16x16x32_bf16 v[12:15], v[178:181], v[212:215], v[12:15]
	v_mfma_f32_16x16x32_bf16 v[4:7], v[170:173], v[220:223], v[4:7]
	v_mfma_f32_16x16x32_bf16 v[0:3], v[178:181], v[220:223], v[0:3]
	s_setprio 0
	s_barrier
	s_add_i32 s59, s59, 2
	s_add_u32 s52, s52, 0x100
	s_addc_u32 s53, s53, 0
	s_add_u32 s6, s6, 0x100
	s_addc_u32 s7, s7, 0
	s_cmp_gt_u32 s59, 13
	s_cbranch_scc0 .LBB0_376
	s_and_b64 vcc, exec, s[24:25]
	s_cbranch_vccz .LBB0_379
	s_barrier

; #define PG8_STAGE(bufoff, gbase, voff) do { _Pragma("unroll") for (int _i = 0; _i < 2; ++_i) \
;         __builtin_amdgcn_global_load_lds((const unsigned*)((const char*)(gbase) + (voff)[_i]), (PG8_LAS unsigned*)(lds + (bufoff) + ldsw + _i * 8192), 16, 0, 0); } while (0)
; #define PG8_LDA(dst, b, h) do { _Pragma("unroll") for (int m = 0; m < 4; ++m) _Pragma("unroll") for (int k = 0; k < 2; ++k) dst[m][k] = *(const PG8_LAS bf16x8*)(lds + PG8_SA(b, h) + aoff + m * 2048 + k * 1024); } while (0)
; #define PG8_LDB(dst, b, h) do { _Pragma("unroll") for (int n = 0; n < 2; ++n) _Pragma("unroll") for (int k = 0; k < 2; ++k) dst[n][k] = *(const PG8_LAS bf16x8*)(lds + PG8_SB(b, h) + boff + n * 2048 + k * 1024); } while (0)
; #define PG8_WAIT_V(n) asm volatile("s_waitcnt vmcnt(" #n ")" ::: "memory")
; #define PG8_WAIT_L(n) asm volatile("s_waitcnt lgkmcnt(" #n ")" ::: "memory")
; #define PG8_BAR __builtin_amdgcn_s_barrier()
; #define PG8_SCHED __builtin_amdgcn_sched_barrier(0)
; template <class Epi, class Sched, bool ALIGN_EPI = false, bool SP2 = true>
; __device__ __forceinline__ void gemm_phase(PG8_LAS unsigned char* lds, const Gemm g, const Sched& S, const Epi& E) {
;     ...
;         const bool has_next = S.next(ui + 1, nxt);
;         const char* nA = has_next ? (const char*)g.A + (size_t)nxt.pm * tstepA + (size_t)nxt.pn * pnA : cA; const char* nB = has_next ? (const char*)g.Bt + (size_t)nxt.pn * tstep : cB;
;         for (int t = 0; t < nt; t += 2) {
;             const bool last = (t == nt - 2);
;             const char* a1 = cA + (size_t)(t + 1) * kstepA;
;             const char* a2 = last ? nA : cA + (size_t)(t + 2) * kstepA; const char* b2 = last ? nB : cB + (size_t)(t + 2) * kstep;
;             const char* a3 = a2 + kstepA; const char* b3 = b2 + kstep;
;             if (last && has_next) S.a_ready(nxt);
;             if constexpr (SP2) {
;             PG8_LDB(B0, 0, 0); PG8_LDB(B1, 0, 1); PG8_SCHED; PG8_LDA(At, 0, 0); PG8_STAGE(PG8_SA(1, 1), a1 + hstepA, voffA);
;             PG8_WAIT_V(8); PG8_WAIT_L(0); PG8_BAR; PG8_MMA(0, 0, At, B0); PG8_MMA(0, 1, At, B1); PG8_BAR; PG8_SCHED;
;     ...
;         for (int a = 0; a < 2; ++a)
; #pragma unroll
;             for (int b = 0; b < 2; ++b)
; #pragma unroll
;                 for (int m = 0; m < 4; ++m)
; #pragma unroll
;                     for (int n = 0; n < 2; ++n) acc[a][b][m][n] = (f32x4){0.f, 0.f, 0.f, 0.f};
.LBB0_744:
	s_ashr_i32 s41, s40, 31
	s_lshl_b64 s[6:7], s[40:41], 19
	s_add_u32 s42, s26, s6
	s_addc_u32 s43, s27, s7
	s_and_b64 s[6:7], s[38:39], exec
	s_cselect_b32 s16, s43, s51
	s_cselect_b32 s17, s42, s50
	s_ashr_i32 s25, s24, 31
	s_lshl_b64 s[6:7], s[24:25], 19
	s_add_u32 s44, s28, s6
	s_addc_u32 s45, s29, s7
	s_and_b64 s[6:7], s[38:39], exec
	s_cselect_b32 s25, s45, s53
	s_cselect_b32 s41, s44, s52
	s_add_u32 s50, s50, 0x40080
	s_addc_u32 s51, s51, 0
	s_add_u32 s6, s52, 0x100
	s_addc_u32 s7, s53, 0
	s_mov_b32 s47, -2
	s_add_u32 s4, s50, 0xfffc0080
	s_addc_u32 s5, s51, -1
	s_add_i32 s14, 0, 0x10000
	s_cmp_eq_u32 s47, 12
	s_cselect_b32 s85, s16, s5
	s_cselect_b32 s84, s17, s4
	s_cselect_b32 s53, s25, s7
	s_cselect_b32 s52, s41, s6
	s_add_i32 s4, 0, 0x14000
	v_add_u32_e32 v146, s14, v173
	v_add_u32_e32 v162, s4, v173
	ds_read_b128 v[134:137], v146
	ds_read_b128 v[138:141], v146 offset:1024
	ds_read_b128 v[142:145], v146 offset:2048
	ds_read_b128 v[146:149], v146 offset:3072
	ds_read_b128 v[150:153], v162
	ds_read_b128 v[154:157], v162 offset:1024
	ds_read_b128 v[158:161], v162 offset:2048
	ds_read_b128 v[162:165], v162 offset:3072
	v_lshl_add_u64 v[170:171], s[50:51], 0, v[130:131]
	s_add_i32 m0, s31, 0xc000
	ds_read_b128 v[166:169], v175
	ds_read_b128 v[176:179], v175 offset:1024
	ds_read_b128 v[180:183], v175 offset:2048
	ds_read_b128 v[184:187], v175 offset:3072
	ds_read_b128 v[188:191], v175 offset:4096
	ds_read_b128 v[200:203], v175 offset:5120
	ds_read_b128 v[204:207], v175 offset:6144
	ds_read_b128 v[208:211], v175 offset:7168
	global_load_lds_dwordx4 v[170:171], off
	v_lshl_add_u64 v[170:171], s[50:51], 0, v[132:133]
	s_add_i32 m0, s31, 0xe000
	s_nop 0
	global_load_lds_dwordx4 v[170:171], off
	s_waitcnt vmcnt(8)
	s_waitcnt lgkmcnt(0)
	s_setprio 1
	s_barrier
	v_mfma_f32_16x16x32_bf16 v[124:127], v[134:137], v[166:169], 0
	v_mfma_f32_16x16x32_bf16 v[120:123], v[142:145], v[166:169], 0
	v_mfma_f32_16x16x32_bf16 v[108:111], v[134:137], v[180:183], 0
	v_mfma_f32_16x16x32_bf16 v[104:107], v[142:145], v[180:183], 0
	v_mfma_f32_16x16x32_bf16 v[92:95], v[134:137], v[188:191], 0
	v_mfma_f32_16x16x32_bf16 v[88:91], v[142:145], v[188:191], 0
	v_mfma_f32_16x16x32_bf16 v[76:79], v[134:137], v[204:207], 0
	v_mfma_f32_16x16x32_bf16 v[72:75], v[142:145], v[204:207], 0
	v_mfma_f32_16x16x32_bf16 v[124:127], v[138:141], v[176:179], v[124:127]
	v_mfma_f32_16x16x32_bf16 v[120:123], v[146:149], v[176:179], v[120:123]
	v_mfma_f32_16x16x32_bf16 v[108:111], v[138:141], v[184:187], v[108:111]
	v_mfma_f32_16x16x32_bf16 v[104:107], v[146:149], v[184:187], v[104:107]
	v_mfma_f32_16x16x32_bf16 v[92:95], v[138:141], v[200:203], v[92:95]
	v_mfma_f32_16x16x32_bf16 v[88:91], v[146:149], v[200:203], v[88:91]
	v_mfma_f32_16x16x32_bf16 v[76:79], v[138:141], v[208:211], v[76:79]
	v_mfma_f32_16x16x32_bf16 v[72:75], v[146:149], v[208:211], v[72:75]
	s_setprio 0
	s_setprio 1
	v_mfma_f32_16x16x32_bf16 v[116:119], v[150:153], v[166:169], 0
	v_mfma_f32_16x16x32_bf16 v[112:115], v[158:161], v[166:169], 0
	v_mfma_f32_16x16x32_bf16 v[100:103], v[150:153], v[180:183], 0
	v_mfma_f32_16x16x32_bf16 v[96:99], v[158:161], v[180:183], 0
	v_mfma_f32_16x16x32_bf16 v[84:87], v[150:153], v[188:191], 0
	v_mfma_f32_16x16x32_bf16 v[80:83], v[158:161], v[188:191], 0
	v_mfma_f32_16x16x32_bf16 v[68:71], v[150:153], v[204:207], 0
	v_mfma_f32_16x16x32_bf16 v[64:67], v[158:161], v[204:207], 0
	v_mfma_f32_16x16x32_bf16 v[116:119], v[154:157], v[176:179], v[116:119]
	v_mfma_f32_16x16x32_bf16 v[112:115], v[162:165], v[176:179], v[112:115]
	v_mfma_f32_16x16x32_bf16 v[100:103], v[154:157], v[184:187], v[100:103]
	v_mfma_f32_16x16x32_bf16 v[96:99], v[162:165], v[184:187], v[96:99]
	v_mfma_f32_16x16x32_bf16 v[84:87], v[154:157], v[200:203], v[84:87]
	v_mfma_f32_16x16x32_bf16 v[80:83], v[162:165], v[200:203], v[80:83]
	v_mfma_f32_16x16x32_bf16 v[68:71], v[154:157], v[208:211], v[68:71]
	v_mfma_f32_16x16x32_bf16 v[64:67], v[162:165], v[208:211], v[64:67]
	s_setprio 0
	s_barrier
; #define PG8_STAGE(bufoff, gbase, voff) do { _Pragma("unroll") for (int _i = 0; _i < 2; ++_i) \
;         __builtin_amdgcn_global_load_lds((const unsigned*)((const char*)(gbase) + (voff)[_i]), (PG8_LAS unsigned*)(lds + (bufoff) + ldsw + _i * 8192), 16, 0, 0); } while (0)
; #define PG8_LDA(dst, b, h) do { _Pragma("unroll") for (int m = 0; m < 4; ++m) _Pragma("unroll") for (int k = 0; k < 2; ++k) dst[m][k] = *(const PG8_LAS bf16x8*)(lds + PG8_SA(b, h) + aoff + m * 2048 + k * 1024); } while (0)
; #define PG8_MMA(ai, bj, At, Bt) do { __builtin_amdgcn_s_setprio(1); _Pragma("unroll") for (int m = 0; m < 4; ++m) _Pragma("unroll") for (int n = 0; n < 2; ++n) _Pragma("unroll") for (int k = 0; k < 2; ++k) \
;         acc[ai][bj][m][n] = __builtin_amdgcn_mfma_f32_16x16x32_bf16(Bt[n][k], At[m][k], acc[ai][bj][m][n], 0, 0, 0); __builtin_amdgcn_s_setprio(0); } while (0)
; #define PG8_WAIT_V(n) asm volatile("s_waitcnt vmcnt(" #n ")" ::: "memory")
; #define PG8_WAIT_L(n) asm volatile("s_waitcnt lgkmcnt(" #n ")" ::: "memory")
; #define PG8_BAR __builtin_amdgcn_s_barrier()
; #define PG8_SCHED __builtin_amdgcn_sched_barrier(0)
; template <class Epi, class Sched, bool ALIGN_EPI = false, bool SP2 = true>
; __device__ __forceinline__ void gemm_phase(PG8_LAS unsigned char* lds, const Gemm g, const Sched& S, const Epi& E) {
;     ...
;             PG8_LDA(At, 0, 1); PG8_STAGE(PG8_SB(0, 0), b2, voffB); PG8_STAGE(PG8_SB(0, 1), b2 + hstep, voffB); PG8_STAGE(PG8_SA(0, 0), a2, voffA);
;             PG8_WAIT_V(8); PG8_WAIT_L(0); PG8_BAR; PG8_MMA(1, 0, At, B0); PG8_MMA(1, 1, At, B1); PG8_BAR; PG8_SCHED;
	s_add_i32 s5, s14, s30
	v_lshl_add_u64 v[170:171], s[52:53], 0, v[194:195]
	s_mov_b32 m0, s5
	ds_read_b128 v[166:169], v175 offset:16384
	ds_read_b128 v[176:179], v175 offset:17408
	ds_read_b128 v[180:183], v175 offset:18432
	ds_read_b128 v[184:187], v175 offset:19456
	ds_read_b128 v[188:191], v175 offset:20480
	ds_read_b128 v[200:203], v175 offset:21504
	ds_read_b128 v[204:207], v175 offset:22528
	ds_read_b128 v[208:211], v175 offset:23552
	global_load_lds_dwordx4 v[170:171], off
	s_add_i32 m0, s5, 0x2000
	s_add_u32 s14, s52, 0x40000
	v_lshl_add_u64 v[198:199], s[52:53], 0, v[128:129]
	s_addc_u32 s15, s53, 0
	s_add_i32 s4, s4, s30
	global_load_lds_dwordx4 v[198:199], off
	v_lshl_add_u64 v[212:213], s[14:15], 0, v[194:195]
	s_mov_b32 m0, s4
	v_lshl_add_u64 v[214:215], s[84:85], 0, v[128:129]
	global_load_lds_dwordx4 v[212:213], off
	v_lshl_add_u64 v[212:213], s[14:15], 0, v[128:129]
	s_add_i32 m0, s4, 0x2000
	s_nop 0
	global_load_lds_dwordx4 v[212:213], off
	v_lshl_add_u64 v[212:213], s[84:85], 0, v[194:195]
	s_mov_b32 m0, s31
	s_nop 0
	global_load_lds_dwordx4 v[212:213], off
	s_mov_b32 m0, s34
	s_nop 0
	global_load_lds_dwordx4 v[214:215], off
	s_waitcnt vmcnt(8)
	s_waitcnt lgkmcnt(0)
	s_setprio 1
	s_barrier
	v_mfma_f32_16x16x32_bf16 v[60:63], v[134:137], v[166:169], 0
	v_mfma_f32_16x16x32_bf16 v[56:59], v[142:145], v[166:169], 0
	v_mfma_f32_16x16x32_bf16 v[44:47], v[134:137], v[180:183], 0
	v_mfma_f32_16x16x32_bf16 v[40:43], v[142:145], v[180:183], 0
	v_mfma_f32_16x16x32_bf16 v[28:31], v[134:137], v[188:191], 0
	v_mfma_f32_16x16x32_bf16 v[24:27], v[142:145], v[188:191], 0
	v_mfma_f32_16x16x32_bf16 v[12:15], v[134:137], v[204:207], 0
	v_mfma_f32_16x16x32_bf16 v[8:11], v[142:145], v[204:207], 0
	v_mfma_f32_16x16x32_bf16 v[60:63], v[138:141], v[176:179], v[60:63]
	v_mfma_f32_16x16x32_bf16 v[56:59], v[146:149], v[176:179], v[56:59]
	v_mfma_f32_16x16x32_bf16 v[44:47], v[138:141], v[184:187], v[44:47]
	v_mfma_f32_16x16x32_bf16 v[40:43], v[146:149], v[184:187], v[40:43]
	v_mfma_f32_16x16x32_bf16 v[28:31], v[138:141], v[200:203], v[28:31]
	v_mfma_f32_16x16x32_bf16 v[24:27], v[146:149], v[200:203], v[24:27]
	v_mfma_f32_16x16x32_bf16 v[12:15], v[138:141], v[208:211], v[12:15]
	v_mfma_f32_16x16x32_bf16 v[8:11], v[146:149], v[208:211], v[8:11]
	s_setprio 0
	s_setprio 1
	v_mfma_f32_16x16x32_bf16 v[52:55], v[150:153], v[166:169], 0
	v_mfma_f32_16x16x32_bf16 v[48:51], v[158:161], v[166:169], 0
	v_mfma_f32_16x16x32_bf16 v[36:39], v[150:153], v[180:183], 0
	v_mfma_f32_16x16x32_bf16 v[32:35], v[158:161], v[180:183], 0
	v_mfma_f32_16x16x32_bf16 v[20:23], v[150:153], v[188:191], 0
	v_mfma_f32_16x16x32_bf16 v[16:19], v[158:161], v[188:191], 0
	v_mfma_f32_16x16x32_bf16 v[4:7], v[150:153], v[204:207], 0
	v_mfma_f32_16x16x32_bf16 v[0:3], v[158:161], v[204:207], 0
	v_mfma_f32_16x16x32_bf16 v[52:55], v[154:157], v[176:179], v[52:55]
	v_mfma_f32_16x16x32_bf16 v[48:51], v[162:165], v[176:179], v[48:51]
	v_mfma_f32_16x16x32_bf16 v[36:39], v[154:157], v[184:187], v[36:39]
	v_mfma_f32_16x16x32_bf16 v[32:35], v[162:165], v[184:187], v[32:35]
	v_mfma_f32_16x16x32_bf16 v[20:23], v[154:157], v[200:203], v[20:23]
	v_mfma_f32_16x16x32_bf16 v[16:19], v[162:165], v[200:203], v[16:19]
	v_mfma_f32_16x16x32_bf16 v[4:7], v[154:157], v[208:211], v[4:7]
	v_mfma_f32_16x16x32_bf16 v[0:3], v[162:165], v[208:211], v[0:3]
	s_setprio 0
	s_barrier
	s_branch .Lmo_s3

; #define PG8_STAGE(bufoff, gbase, voff) do { _Pragma("unroll") for (int _i = 0; _i < 2; ++_i) \
;         __builtin_amdgcn_global_load_lds((const unsigned*)((const char*)(gbase) + (voff)[_i]), (PG8_LAS unsigned*)(lds + (bufoff) + ldsw + _i * 8192), 16, 0, 0); } while (0)
; #define PG8_LDA(dst, b, h) do { _Pragma("unroll") for (int m = 0; m < 4; ++m) _Pragma("unroll") for (int k = 0; k < 2; ++k) dst[m][k] = *(const PG8_LAS bf16x8*)(lds + PG8_SA(b, h) + aoff + m * 2048 + k * 1024); } while (0)
; #define PG8_LDB(dst, b, h) do { _Pragma("unroll") for (int n = 0; n < 2; ++n) _Pragma("unroll") for (int k = 0; k < 2; ++k) dst[n][k] = *(const PG8_LAS bf16x8*)(lds + PG8_SB(b, h) + boff + n * 2048 + k * 1024); } while (0)
; #define PG8_MMA(ai, bj, At, Bt) do { __builtin_amdgcn_s_setprio(1); _Pragma("unroll") for (int m = 0; m < 4; ++m) _Pragma("unroll") for (int n = 0; n < 2; ++n) _Pragma("unroll") for (int k = 0; k < 2; ++k) \
;         acc[ai][bj][m][n] = __builtin_amdgcn_mfma_f32_16x16x32_bf16(Bt[n][k], At[m][k], acc[ai][bj][m][n], 0, 0, 0); __builtin_amdgcn_s_setprio(0); } while (0)
; #define PG8_WAIT_V(n) asm volatile("s_waitcnt vmcnt(" #n ")" ::: "memory")
; #define PG8_WAIT_L(n) asm volatile("s_waitcnt lgkmcnt(" #n ")" ::: "memory")
; #define PG8_BAR __builtin_amdgcn_s_barrier()
; #define PG8_SCHED __builtin_amdgcn_sched_barrier(0)
; template <class Epi, class Sched, bool ALIGN_EPI = false, bool SP2 = true>
; __device__ __forceinline__ void gemm_phase(PG8_LAS unsigned char* lds, const Gemm g, const Sched& S, const Epi& E) {
;     ...
;             PG8_LDB(B0, 1, 0); PG8_LDB(B1, 1, 1); PG8_SCHED; PG8_LDA(At, 1, 0); PG8_STAGE(PG8_SA(0, 1), a2 + hstepA, voffA);
;             PG8_WAIT_V(8); PG8_WAIT_L(0); PG8_BAR; PG8_MMA(0, 0, At, B0); PG8_MMA(0, 1, At, B1); PG8_BAR; PG8_SCHED;
.Lmo_s3:
	s_add_i32 s4, 0, 0x18000
	s_add_i32 s5, 0, 0x1c000
	v_add_u32_e32 v146, s4, v173
	v_add_u32_e32 v162, s5, v173
	ds_read_b128 v[134:137], v146
	ds_read_b128 v[138:141], v146 offset:1024
	ds_read_b128 v[142:145], v146 offset:2048
	ds_read_b128 v[146:149], v146 offset:3072
	ds_read_b128 v[150:153], v162
	ds_read_b128 v[154:157], v162 offset:1024
	ds_read_b128 v[158:161], v162 offset:2048
	ds_read_b128 v[162:165], v162 offset:3072
	s_add_u32 s14, s84, 0x40000
	s_addc_u32 s15, s85, 0
	s_mov_b32 m0, s35
	v_lshl_add_u64 v[216:217], s[14:15], 0, v[194:195]
	ds_read_b128 v[166:169], v175 offset:32768
	ds_read_b128 v[176:179], v175 offset:33792
	ds_read_b128 v[180:183], v175 offset:34816
	ds_read_b128 v[184:187], v175 offset:35840
	ds_read_b128 v[188:191], v175 offset:36864
	ds_read_b128 v[200:203], v175 offset:37888
	ds_read_b128 v[204:207], v175 offset:38912
	ds_read_b128 v[208:211], v175 offset:39936
	global_load_lds_dwordx4 v[216:217], off
	v_lshl_add_u64 v[216:217], s[14:15], 0, v[128:129]
	s_mov_b32 m0, s49
	s_nop 0
	global_load_lds_dwordx4 v[216:217], off
	s_waitcnt vmcnt(8)
	s_waitcnt lgkmcnt(0)
	s_setprio 1
	s_barrier
	v_mfma_f32_16x16x32_bf16 v[124:127], v[134:137], v[166:169], v[124:127]
	v_mfma_f32_16x16x32_bf16 v[120:123], v[142:145], v[166:169], v[120:123]
	v_mfma_f32_16x16x32_bf16 v[108:111], v[134:137], v[180:183], v[108:111]
	v_mfma_f32_16x16x32_bf16 v[104:107], v[142:145], v[180:183], v[104:107]
	v_mfma_f32_16x16x32_bf16 v[92:95], v[134:137], v[188:191], v[92:95]
	v_mfma_f32_16x16x32_bf16 v[88:91], v[142:145], v[188:191], v[88:91]
	v_mfma_f32_16x16x32_bf16 v[76:79], v[134:137], v[204:207], v[76:79]
	v_mfma_f32_16x16x32_bf16 v[72:75], v[142:145], v[204:207], v[72:75]
	v_mfma_f32_16x16x32_bf16 v[124:127], v[138:141], v[176:179], v[124:127]
	v_mfma_f32_16x16x32_bf16 v[120:123], v[146:149], v[176:179], v[120:123]
	v_mfma_f32_16x16x32_bf16 v[108:111], v[138:141], v[184:187], v[108:111]
	v_mfma_f32_16x16x32_bf16 v[104:107], v[146:149], v[184:187], v[104:107]
	v_mfma_f32_16x16x32_bf16 v[92:95], v[138:141], v[200:203], v[92:95]
	v_mfma_f32_16x16x32_bf16 v[88:91], v[146:149], v[200:203], v[88:91]
	v_mfma_f32_16x16x32_bf16 v[76:79], v[138:141], v[208:211], v[76:79]
	v_mfma_f32_16x16x32_bf16 v[72:75], v[146:149], v[208:211], v[72:75]
	s_setprio 0
	s_setprio 1
	v_mfma_f32_16x16x32_bf16 v[116:119], v[150:153], v[166:169], v[116:119]
	v_mfma_f32_16x16x32_bf16 v[112:115], v[158:161], v[166:169], v[112:115]
	v_mfma_f32_16x16x32_bf16 v[100:103], v[150:153], v[180:183], v[100:103]
	v_mfma_f32_16x16x32_bf16 v[96:99], v[158:161], v[180:183], v[96:99]
	v_mfma_f32_16x16x32_bf16 v[84:87], v[150:153], v[188:191], v[84:87]
	v_mfma_f32_16x16x32_bf16 v[80:83], v[158:161], v[188:191], v[80:83]
	v_mfma_f32_16x16x32_bf16 v[68:71], v[150:153], v[204:207], v[68:71]
	v_mfma_f32_16x16x32_bf16 v[64:67], v[158:161], v[204:207], v[64:67]
	v_mfma_f32_16x16x32_bf16 v[116:119], v[154:157], v[176:179], v[116:119]
	v_mfma_f32_16x16x32_bf16 v[112:115], v[162:165], v[176:179], v[112:115]
	v_mfma_f32_16x16x32_bf16 v[100:103], v[154:157], v[184:187], v[100:103]
	v_mfma_f32_16x16x32_bf16 v[96:99], v[162:165], v[184:187], v[96:99]
	v_mfma_f32_16x16x32_bf16 v[84:87], v[154:157], v[200:203], v[84:87]
	v_mfma_f32_16x16x32_bf16 v[80:83], v[162:165], v[200:203], v[80:83]
	v_mfma_f32_16x16x32_bf16 v[68:71], v[154:157], v[208:211], v[68:71]
	v_mfma_f32_16x16x32_bf16 v[64:67], v[162:165], v[208:211], v[64:67]
	s_setprio 0
	s_barrier
; #define PG8_STAGE(bufoff, gbase, voff) do { _Pragma("unroll") for (int _i = 0; _i < 2; ++_i) \
;         __builtin_amdgcn_global_load_lds((const unsigned*)((const char*)(gbase) + (voff)[_i]), (PG8_LAS unsigned*)(lds + (bufoff) + ldsw + _i * 8192), 16, 0, 0); } while (0)
; #define PG8_LDA(dst, b, h) do { _Pragma("unroll") for (int m = 0; m < 4; ++m) _Pragma("unroll") for (int k = 0; k < 2; ++k) dst[m][k] = *(const PG8_LAS bf16x8*)(lds + PG8_SA(b, h) + aoff + m * 2048 + k * 1024); } while (0)
; #define PG8_MMA(ai, bj, At, Bt) do { __builtin_amdgcn_s_setprio(1); _Pragma("unroll") for (int m = 0; m < 4; ++m) _Pragma("unroll") for (int n = 0; n < 2; ++n) _Pragma("unroll") for (int k = 0; k < 2; ++k) \
;         acc[ai][bj][m][n] = __builtin_amdgcn_mfma_f32_16x16x32_bf16(Bt[n][k], At[m][k], acc[ai][bj][m][n], 0, 0, 0); __builtin_amdgcn_s_setprio(0); } while (0)
; #define PG8_WAIT_V(n) asm volatile("s_waitcnt vmcnt(" #n ")" ::: "memory")
; #define PG8_WAIT_L(n) asm volatile("s_waitcnt lgkmcnt(" #n ")" ::: "memory")
; #define PG8_BAR __builtin_amdgcn_s_barrier()
; #define PG8_SCHED __builtin_amdgcn_sched_barrier(0)
; template <class Epi, class Sched, bool ALIGN_EPI = false, bool SP2 = true>
; __device__ __forceinline__ void gemm_phase(PG8_LAS unsigned char* lds, const Gemm g, const Sched& S, const Epi& E) {
;     ...
;             PG8_LDA(At, 1, 1); PG8_STAGE(PG8_SB(1, 0), b3, voffB); PG8_STAGE(PG8_SB(1, 1), b3 + hstep, voffB); PG8_STAGE(PG8_SA(1, 0), a3, voffA);
;             PG8_WAIT_V(8); PG8_WAIT_L(0); PG8_BAR; PG8_MMA(1, 0, At, B0); PG8_MMA(1, 1, At, B1); PG8_BAR; PG8_SCHED;
;     ...
;         if constexpr (ALIGN_EPI) { if (wr == 0) PG8_BAR; }
	s_add_i32 s4, s4, s30
	v_lshl_add_u64 v[170:171], v[170:171], 0, s[18:19]
	s_mov_b32 m0, s4
	ds_read_b128 v[166:169], v175 offset:49152
	ds_read_b128 v[176:179], v175 offset:50176
	ds_read_b128 v[180:183], v175 offset:51200
	ds_read_b128 v[184:187], v175 offset:52224
	ds_read_b128 v[188:191], v175 offset:53248
	ds_read_b128 v[200:203], v175 offset:54272
	ds_read_b128 v[204:207], v175 offset:55296
	ds_read_b128 v[208:211], v175 offset:56320
	global_load_lds_dwordx4 v[170:171], off
	s_add_i32 m0, s4, 0x2000
	s_add_u32 s14, s52, 0x40080
	v_lshl_add_u64 v[170:171], v[198:199], 0, s[18:19]
	s_addc_u32 s15, s53, 0
	s_add_i32 s4, s5, s30
	global_load_lds_dwordx4 v[170:171], off
	v_lshl_add_u64 v[170:171], s[14:15], 0, v[194:195]
	s_mov_b32 m0, s4
	s_nop 0
	global_load_lds_dwordx4 v[170:171], off
	v_lshl_add_u64 v[170:171], s[14:15], 0, v[128:129]
	s_add_i32 m0, s4, 0x2000
	s_nop 0
	global_load_lds_dwordx4 v[170:171], off
	v_lshl_add_u64 v[170:171], v[212:213], 0, s[18:19]
	s_mov_b32 m0, s57
	s_nop 0
	global_load_lds_dwordx4 v[170:171], off
	v_lshl_add_u64 v[170:171], v[214:215], 0, s[18:19]
	s_mov_b32 m0, s59
	s_nop 0
	global_load_lds_dwordx4 v[170:171], off
	s_waitcnt vmcnt(8)
	s_waitcnt lgkmcnt(0)
	s_setprio 1
	s_barrier
	v_mfma_f32_16x16x32_bf16 v[60:63], v[134:137], v[166:169], v[60:63]
	v_mfma_f32_16x16x32_bf16 v[56:59], v[142:145], v[166:169], v[56:59]
	v_mfma_f32_16x16x32_bf16 v[44:47], v[134:137], v[180:183], v[44:47]
	v_mfma_f32_16x16x32_bf16 v[40:43], v[142:145], v[180:183], v[40:43]
	v_mfma_f32_16x16x32_bf16 v[28:31], v[134:137], v[188:191], v[28:31]
	v_mfma_f32_16x16x32_bf16 v[24:27], v[142:145], v[188:191], v[24:27]
	v_mfma_f32_16x16x32_bf16 v[12:15], v[134:137], v[204:207], v[12:15]
	v_mfma_f32_16x16x32_bf16 v[8:11], v[142:145], v[204:207], v[8:11]
	v_mfma_f32_16x16x32_bf16 v[60:63], v[138:141], v[176:179], v[60:63]
	v_mfma_f32_16x16x32_bf16 v[56:59], v[146:149], v[176:179], v[56:59]
	v_mfma_f32_16x16x32_bf16 v[44:47], v[138:141], v[184:187], v[44:47]
	v_mfma_f32_16x16x32_bf16 v[40:43], v[146:149], v[184:187], v[40:43]
	v_mfma_f32_16x16x32_bf16 v[28:31], v[138:141], v[200:203], v[28:31]
	v_mfma_f32_16x16x32_bf16 v[24:27], v[146:149], v[200:203], v[24:27]
	v_mfma_f32_16x16x32_bf16 v[12:15], v[138:141], v[208:211], v[12:15]
	v_mfma_f32_16x16x32_bf16 v[8:11], v[146:149], v[208:211], v[8:11]
	s_setprio 0
	s_setprio 1
	v_mfma_f32_16x16x32_bf16 v[52:55], v[150:153], v[166:169], v[52:55]
	v_mfma_f32_16x16x32_bf16 v[48:51], v[158:161], v[166:169], v[48:51]
	v_mfma_f32_16x16x32_bf16 v[36:39], v[150:153], v[180:183], v[36:39]
	v_mfma_f32_16x16x32_bf16 v[32:35], v[158:161], v[180:183], v[32:35]
	v_mfma_f32_16x16x32_bf16 v[20:23], v[150:153], v[188:191], v[20:23]
	v_mfma_f32_16x16x32_bf16 v[16:19], v[158:161], v[188:191], v[16:19]
	v_mfma_f32_16x16x32_bf16 v[4:7], v[150:153], v[204:207], v[4:7]
	v_mfma_f32_16x16x32_bf16 v[0:3], v[158:161], v[204:207], v[0:3]
	v_mfma_f32_16x16x32_bf16 v[52:55], v[154:157], v[176:179], v[52:55]
	v_mfma_f32_16x16x32_bf16 v[48:51], v[162:165], v[176:179], v[48:51]
	v_mfma_f32_16x16x32_bf16 v[36:39], v[154:157], v[184:187], v[36:39]
	v_mfma_f32_16x16x32_bf16 v[32:35], v[162:165], v[184:187], v[32:35]
	v_mfma_f32_16x16x32_bf16 v[20:23], v[154:157], v[200:203], v[20:23]
	v_mfma_f32_16x16x32_bf16 v[16:19], v[162:165], v[200:203], v[16:19]
	v_mfma_f32_16x16x32_bf16 v[4:7], v[154:157], v[208:211], v[4:7]
	v_mfma_f32_16x16x32_bf16 v[0:3], v[162:165], v[208:211], v[0:3]
	s_setprio 0
	s_barrier
	s_add_i32 s47, s47, 2
	s_add_u32 s50, s50, 0x100
	s_addc_u32 s51, s51, 0
	s_add_u32 s6, s6, 0x100
	s_addc_u32 s7, s7, 0
	s_cmp_gt_u32 s47, 13
	s_cbranch_scc0 .LBB0_745
	s_and_b64 vcc, exec, s[20:21]
	s_cbranch_vccz .LBB0_748
	s_barrier
